# v34: ssq loads of EpiUp/EpiProj (phases 1,3,8) hoisted to tile head before the K loop into v246-253; epilogue vmcnt(0) replaced by vmcnt(30)
# baseline (speedup 1.0000x reference)
.LBB0_172:
	v_lshl_add_u32 v254, s14, 8, v138
	v_ashrrev_i32_e32 v255, 31, v254
	v_lshl_add_u64 v[254:255], v[254:255], 2, s[84:85]
	global_load_dword v246, v[254:255], off
	global_load_dword v247, v[254:255], off offset:64
	global_load_dword v248, v[254:255], off offset:128
	global_load_dword v249, v[254:255], off offset:192
	global_load_dword v250, v[254:255], off offset:512
	global_load_dword v251, v[254:255], off offset:576
	global_load_dword v252, v[254:255], off offset:640
	global_load_dword v253, v[254:255], off offset:704
	s_add_u32 s28, s28, 0x40080
	s_addc_u32 s29, s29, 0
	s_add_u32 s9, s30, 0x100
	v_mov_b32_e32 v0, 0
	s_addc_u32 s60, s31, 0
	s_mov_b32 s61, -2
	v_mov_b32_e32 v1, v0
	v_mov_b32_e32 v2, v0
	v_mov_b32_e32 v3, v0
	v_mov_b32_e32 v4, v0
	v_mov_b32_e32 v5, v0
	v_mov_b32_e32 v6, v0
	v_mov_b32_e32 v7, v0
	v_mov_b32_e32 v16, v0
	v_mov_b32_e32 v17, v0
	v_mov_b32_e32 v18, v0
	v_mov_b32_e32 v19, v0
	v_mov_b32_e32 v20, v0
	v_mov_b32_e32 v21, v0
	v_mov_b32_e32 v22, v0
	v_mov_b32_e32 v23, v0
	v_mov_b32_e32 v32, v0
	v_mov_b32_e32 v33, v0
	v_mov_b32_e32 v34, v0
	v_mov_b32_e32 v35, v0
	v_mov_b32_e32 v36, v0
	v_mov_b32_e32 v37, v0
	v_mov_b32_e32 v38, v0
	v_mov_b32_e32 v39, v0
	v_mov_b32_e32 v48, v0
	s_waitcnt lgkmcnt(0)
	v_mov_b32_e32 v49, v0
	v_mov_b32_e32 v50, v0
	v_mov_b32_e32 v51, v0
	v_mov_b32_e32 v52, v0
	v_mov_b32_e32 v53, v0
	v_mov_b32_e32 v54, v0
	v_mov_b32_e32 v55, v0
	v_mov_b32_e32 v8, v0
	v_mov_b32_e32 v9, v0
	v_mov_b32_e32 v10, v0
	v_mov_b32_e32 v11, v0
	v_mov_b32_e32 v12, v0
	v_mov_b32_e32 v13, v0
	v_mov_b32_e32 v14, v0
	v_mov_b32_e32 v15, v0
	v_mov_b32_e32 v24, v0
	v_mov_b32_e32 v25, v0
	v_mov_b32_e32 v26, v0
	v_mov_b32_e32 v27, v0
	v_mov_b32_e32 v28, v0
	v_mov_b32_e32 v29, v0
	v_mov_b32_e32 v30, v0
	v_mov_b32_e32 v31, v0
	v_mov_b32_e32 v40, v0
	v_mov_b32_e32 v41, v0
	v_mov_b32_e32 v42, v0
	v_mov_b32_e32 v43, v0
	v_mov_b32_e32 v44, v0
	v_mov_b32_e32 v45, v0
	v_mov_b32_e32 v46, v0
	v_mov_b32_e32 v47, v0
	v_mov_b32_e32 v56, v0
	v_mov_b32_e32 v57, v0
	v_mov_b32_e32 v58, v0
	v_mov_b32_e32 v59, v0
	v_mov_b32_e32 v60, v0
	v_mov_b32_e32 v61, v0
	v_mov_b32_e32 v62, v0
	v_mov_b32_e32 v63, v0
	v_mov_b32_e32 v64, v0
	v_mov_b32_e32 v65, v0
	v_mov_b32_e32 v66, v0
	v_mov_b32_e32 v67, v0
	v_mov_b32_e32 v68, v0
	v_mov_b32_e32 v69, v0
	v_mov_b32_e32 v70, v0
	v_mov_b32_e32 v71, v0
	v_mov_b32_e32 v80, v0
	v_mov_b32_e32 v81, v0
	v_mov_b32_e32 v82, v0
	v_mov_b32_e32 v83, v0
	v_mov_b32_e32 v84, v0
	v_mov_b32_e32 v85, v0
	v_mov_b32_e32 v86, v0
	v_mov_b32_e32 v87, v0
	v_mov_b32_e32 v96, v0
	v_mov_b32_e32 v97, v0
	v_mov_b32_e32 v98, v0
	v_mov_b32_e32 v99, v0
	v_mov_b32_e32 v100, v0
	v_mov_b32_e32 v101, v0
	v_mov_b32_e32 v102, v0
	v_mov_b32_e32 v103, v0
	v_mov_b32_e32 v112, v0
	v_mov_b32_e32 v113, v0
	v_mov_b32_e32 v114, v0
	v_mov_b32_e32 v115, v0
	v_mov_b32_e32 v116, v0
	v_mov_b32_e32 v117, v0
	v_mov_b32_e32 v118, v0
	v_mov_b32_e32 v119, v0
	v_mov_b32_e32 v72, v0
	v_mov_b32_e32 v73, v0
	v_mov_b32_e32 v74, v0
	v_mov_b32_e32 v75, v0
	v_mov_b32_e32 v76, v0
	v_mov_b32_e32 v77, v0
	v_mov_b32_e32 v78, v0
	v_mov_b32_e32 v79, v0
	v_mov_b32_e32 v88, v0
	v_mov_b32_e32 v89, v0
	v_mov_b32_e32 v90, v0
	v_mov_b32_e32 v91, v0
	v_mov_b32_e32 v92, v0
	v_mov_b32_e32 v93, v0
	v_mov_b32_e32 v94, v0
	v_mov_b32_e32 v95, v0
	v_mov_b32_e32 v104, v0
	v_mov_b32_e32 v105, v0
	v_mov_b32_e32 v106, v0
	v_mov_b32_e32 v107, v0
	v_mov_b32_e32 v108, v0
	v_mov_b32_e32 v109, v0
	v_mov_b32_e32 v110, v0
	v_mov_b32_e32 v111, v0
	v_mov_b32_e32 v120, v0
	v_mov_b32_e32 v121, v0
	v_mov_b32_e32 v122, v0
	v_mov_b32_e32 v123, v0
	v_mov_b32_e32 v124, v0
	v_mov_b32_e32 v125, v0
	v_mov_b32_e32 v126, v0
	v_mov_b32_e32 v127, v0

.LBB0_176:
	v_lshl_add_u32 v164, s14, 8, v138
	v_ashrrev_i32_e32 v165, 31, v164
	v_lshl_add_u64 v[164:165], v[164:165], 2, s[84:85]
	s_lshl_b32 s9, s15, 1
	s_mul_i32 s14, s14, 44
	s_add_i32 s14, s14, s9
	s_or_b32 s14, s14, s53
	s_ashr_i32 s15, s14, 31
	s_lshl_b64 s[14:15], s[14:15], 15
	s_add_u32 s14, s80, s14
	s_addc_u32 s15, s81, s15
	s_waitcnt vmcnt(30)
	v_fmamk_f32 v170, v246, 0x3a800000, v169
	v_cmp_gt_f32_e32 vcc, s58, v170
	v_mul_f32_e32 v171, 0x4b800000, v170
	s_nop 0
	v_cndmask_b32_e32 v170, v170, v171, vcc
	v_rsq_f32_e32 v170, v170
	s_nop 0
	v_mul_f32_e32 v171, 0x45800000, v170
	v_cndmask_b32_e32 v170, v170, v171, vcc
	v_pk_mul_f32 v[124:125], v[124:125], v[170:171] op_sel_hi:[1,0]
	s_nop 0
	v_mul_f32_e32 v171, 0xbfb8aa3b, v124
	v_exp_f32_e32 v171, v171
	s_nop 0
	v_add_f32_e32 v171, 1.0, v171
	v_rcp_f32_e32 v172, v171
	v_pk_mul_f32 v[116:117], v[116:117], v[170:171] op_sel_hi:[1,0]
	v_mul_f32_e32 v171, 0xbfb8aa3b, v125
	v_exp_f32_e32 v171, v171
	s_nop 0
	v_add_f32_e32 v171, 1.0, v171
	v_rcp_f32_e32 v173, v171
	v_pk_mul_f32 v[118:119], v[118:119], v[170:171] op_sel_hi:[1,0]
	v_pk_mul_f32 v[120:121], v[120:121], v[170:171] op_sel_hi:[1,0]
	v_pk_mul_f32 v[112:113], v[112:113], v[170:171] op_sel_hi:[1,0]
	v_pk_mul_f32 v[124:125], v[124:125], v[172:173]
	v_pk_mul_f32 v[114:115], v[114:115], v[170:171] op_sel_hi:[1,0]
	v_pk_mul_f32 v[116:117], v[116:117], v[124:125]
	v_pk_mul_f32 v[124:125], v[126:127], v[170:171] op_sel_hi:[1,0]
	s_nop 0
	v_mul_f32_e32 v126, 0xbfb8aa3b, v124
	v_mul_f32_e32 v127, 0xbfb8aa3b, v125
	v_exp_f32_e32 v126, v126
	v_exp_f32_e32 v127, v127
	v_add_f32_e32 v126, 1.0, v126
	v_add_f32_e32 v127, 1.0, v127
	v_rcp_f32_e32 v126, v126
	v_rcp_f32_e32 v127, v127
	s_nop 0
	v_pk_mul_f32 v[124:125], v[124:125], v[126:127]
	s_nop 0
	v_pk_mul_f32 v[118:119], v[118:119], v[124:125]
	v_mul_f32_e32 v124, 0xbfb8aa3b, v120
	v_mul_f32_e32 v125, 0xbfb8aa3b, v121
	v_exp_f32_e32 v124, v124
	v_exp_f32_e32 v125, v125
	v_add_f32_e32 v124, 1.0, v124
	v_add_f32_e32 v125, 1.0, v125
	v_rcp_f32_e32 v124, v124
	v_rcp_f32_e32 v125, v125
	s_nop 0
	v_pk_mul_f32 v[120:121], v[120:121], v[124:125]
	s_nop 0
	v_pk_mul_f32 v[120:121], v[112:113], v[120:121]
	v_pk_mul_f32 v[112:113], v[122:123], v[170:171] op_sel_hi:[1,0]
	s_nop 0
	v_mul_f32_e32 v122, 0xbfb8aa3b, v112
	v_mul_f32_e32 v123, 0xbfb8aa3b, v113
	v_exp_f32_e32 v122, v122
	v_exp_f32_e32 v123, v123
	v_add_f32_e32 v122, 1.0, v122
	v_add_f32_e32 v123, 1.0, v123
	v_rcp_f32_e32 v122, v122
	v_rcp_f32_e32 v123, v123
	s_nop 0
	v_pk_mul_f32 v[112:113], v[112:113], v[122:123]
	s_nop 0
	v_pk_mul_f32 v[122:123], v[114:115], v[112:113]
	v_cvt_pk_bf16_f32 v112, v116, v117
	v_lshl_add_u64 v[116:117], s[14:15], 0, v[140:141]
	v_cvt_pk_bf16_f32 v113, v118, v119
	v_cvt_pk_bf16_f32 v114, v120, v121
	v_cvt_pk_bf16_f32 v115, v122, v123
	v_lshl_add_u64 v[116:117], v[116:117], 0, v[136:137]
	global_store_dwordx4 v[116:117], v[112:115], off nt
	s_nop 1
	v_fmamk_f32 v112, v247, 0x3a800000, v169
	v_cmp_gt_f32_e32 vcc, s58, v112
	v_mul_f32_e32 v113, 0x4b800000, v112
	s_nop 0
	v_cndmask_b32_e32 v112, v112, v113, vcc
	v_rsq_f32_e32 v112, v112
	s_nop 0
	v_mul_f32_e32 v113, 0x45800000, v112
	v_cndmask_b32_e32 v112, v112, v113, vcc
	v_pk_mul_f32 v[108:109], v[108:109], v[112:113] op_sel_hi:[1,0]
	s_nop 0
	v_mul_f32_e32 v113, 0xbfb8aa3b, v108
	v_exp_f32_e32 v113, v113
	s_nop 0
	v_add_f32_e32 v113, 1.0, v113
	v_rcp_f32_e32 v114, v113
	v_pk_mul_f32 v[100:101], v[100:101], v[112:113] op_sel_hi:[1,0]
	v_mul_f32_e32 v113, 0xbfb8aa3b, v109
	v_exp_f32_e32 v113, v113
	s_nop 0
	v_add_f32_e32 v113, 1.0, v113
	v_rcp_f32_e32 v115, v113
	v_pk_mul_f32 v[102:103], v[102:103], v[112:113] op_sel_hi:[1,0]
	v_pk_mul_f32 v[104:105], v[104:105], v[112:113] op_sel_hi:[1,0]
	v_pk_mul_f32 v[96:97], v[96:97], v[112:113] op_sel_hi:[1,0]
	v_pk_mul_f32 v[108:109], v[108:109], v[114:115]
	v_pk_mul_f32 v[98:99], v[98:99], v[112:113] op_sel_hi:[1,0]
	v_pk_mul_f32 v[100:101], v[100:101], v[108:109]
	v_pk_mul_f32 v[108:109], v[110:111], v[112:113] op_sel_hi:[1,0]
	s_nop 0
	v_mul_f32_e32 v110, 0xbfb8aa3b, v108
	v_mul_f32_e32 v111, 0xbfb8aa3b, v109
	v_exp_f32_e32 v110, v110
	v_exp_f32_e32 v111, v111
	v_add_f32_e32 v110, 1.0, v110
	v_add_f32_e32 v111, 1.0, v111
	v_rcp_f32_e32 v110, v110
	v_rcp_f32_e32 v111, v111
	s_nop 0
	v_pk_mul_f32 v[108:109], v[108:109], v[110:111]
	s_nop 0
	v_pk_mul_f32 v[102:103], v[102:103], v[108:109]
	v_mul_f32_e32 v108, 0xbfb8aa3b, v104
	v_mul_f32_e32 v109, 0xbfb8aa3b, v105
	v_exp_f32_e32 v108, v108
	v_exp_f32_e32 v109, v109
	v_add_f32_e32 v108, 1.0, v108
	v_add_f32_e32 v109, 1.0, v109
	v_rcp_f32_e32 v108, v108
	v_rcp_f32_e32 v109, v109
	s_nop 0
	v_pk_mul_f32 v[104:105], v[104:105], v[108:109]
	s_nop 0
	v_pk_mul_f32 v[104:105], v[96:97], v[104:105]
	v_pk_mul_f32 v[96:97], v[106:107], v[112:113] op_sel_hi:[1,0]
	s_nop 0
	v_mul_f32_e32 v106, 0xbfb8aa3b, v96
	v_mul_f32_e32 v107, 0xbfb8aa3b, v97
	v_exp_f32_e32 v106, v106
	v_exp_f32_e32 v107, v107
	v_add_f32_e32 v106, 1.0, v106
	v_add_f32_e32 v107, 1.0, v107
	v_rcp_f32_e32 v106, v106
	v_rcp_f32_e32 v107, v107
	s_nop 0
	v_pk_mul_f32 v[96:97], v[96:97], v[106:107]
	s_nop 0
	v_pk_mul_f32 v[106:107], v[98:99], v[96:97]
	v_cvt_pk_bf16_f32 v96, v100, v101
	v_lshl_add_u64 v[100:101], s[14:15], 0, v[142:143]
	v_cvt_pk_bf16_f32 v97, v102, v103
	v_cvt_pk_bf16_f32 v98, v104, v105
	v_cvt_pk_bf16_f32 v99, v106, v107
	v_lshl_add_u64 v[100:101], v[100:101], 0, v[136:137]
	global_store_dwordx4 v[100:101], v[96:99], off nt
	s_nop 1
	v_fmamk_f32 v96, v248, 0x3a800000, v169
	v_cmp_gt_f32_e32 vcc, s58, v96
	v_mul_f32_e32 v97, 0x4b800000, v96
	s_nop 0
	v_cndmask_b32_e32 v96, v96, v97, vcc
	v_rsq_f32_e32 v96, v96
	s_nop 0
	v_mul_f32_e32 v97, 0x45800000, v96
	v_cndmask_b32_e32 v96, v96, v97, vcc
	v_pk_mul_f32 v[92:93], v[92:93], v[96:97] op_sel_hi:[1,0]
	s_nop 0
	v_mul_f32_e32 v97, 0xbfb8aa3b, v92
	v_exp_f32_e32 v97, v97
	s_nop 0
	v_add_f32_e32 v97, 1.0, v97
	v_rcp_f32_e32 v98, v97
	v_pk_mul_f32 v[84:85], v[84:85], v[96:97] op_sel_hi:[1,0]
	v_mul_f32_e32 v97, 0xbfb8aa3b, v93
	v_exp_f32_e32 v97, v97
	s_nop 0
	v_add_f32_e32 v97, 1.0, v97
	v_rcp_f32_e32 v99, v97
	v_pk_mul_f32 v[86:87], v[86:87], v[96:97] op_sel_hi:[1,0]
	v_pk_mul_f32 v[88:89], v[88:89], v[96:97] op_sel_hi:[1,0]
	v_pk_mul_f32 v[80:81], v[80:81], v[96:97] op_sel_hi:[1,0]
	v_pk_mul_f32 v[92:93], v[92:93], v[98:99]
	v_pk_mul_f32 v[82:83], v[82:83], v[96:97] op_sel_hi:[1,0]
	v_pk_mul_f32 v[84:85], v[84:85], v[92:93]
	v_pk_mul_f32 v[92:93], v[94:95], v[96:97] op_sel_hi:[1,0]
	s_nop 0
	v_mul_f32_e32 v94, 0xbfb8aa3b, v92
	v_mul_f32_e32 v95, 0xbfb8aa3b, v93
	v_exp_f32_e32 v94, v94
	v_exp_f32_e32 v95, v95
	v_add_f32_e32 v94, 1.0, v94
	v_add_f32_e32 v95, 1.0, v95
	v_rcp_f32_e32 v94, v94
	v_rcp_f32_e32 v95, v95
	s_nop 0
	v_pk_mul_f32 v[92:93], v[92:93], v[94:95]
	s_nop 0
	v_pk_mul_f32 v[86:87], v[86:87], v[92:93]
	v_mul_f32_e32 v92, 0xbfb8aa3b, v88
	v_mul_f32_e32 v93, 0xbfb8aa3b, v89
	v_exp_f32_e32 v92, v92
	v_exp_f32_e32 v93, v93
	v_add_f32_e32 v92, 1.0, v92
	v_add_f32_e32 v93, 1.0, v93
	v_rcp_f32_e32 v92, v92
	v_rcp_f32_e32 v93, v93
	s_nop 0
	v_pk_mul_f32 v[88:89], v[88:89], v[92:93]
	s_nop 0
	v_pk_mul_f32 v[88:89], v[80:81], v[88:89]
	v_pk_mul_f32 v[80:81], v[90:91], v[96:97] op_sel_hi:[1,0]
	s_nop 0
	v_mul_f32_e32 v90, 0xbfb8aa3b, v80
	v_mul_f32_e32 v91, 0xbfb8aa3b, v81
	v_exp_f32_e32 v90, v90
	v_exp_f32_e32 v91, v91
	v_add_f32_e32 v90, 1.0, v90
	v_add_f32_e32 v91, 1.0, v91
	v_rcp_f32_e32 v90, v90
	v_rcp_f32_e32 v91, v91
	s_nop 0
	v_pk_mul_f32 v[80:81], v[80:81], v[90:91]
	s_nop 0
	v_pk_mul_f32 v[90:91], v[82:83], v[80:81]
	v_cvt_pk_bf16_f32 v80, v84, v85
	v_lshl_add_u64 v[84:85], s[14:15], 0, v[144:145]
	v_cvt_pk_bf16_f32 v81, v86, v87
	v_cvt_pk_bf16_f32 v82, v88, v89
	v_cvt_pk_bf16_f32 v83, v90, v91
	v_lshl_add_u64 v[84:85], v[84:85], 0, v[136:137]
	global_store_dwordx4 v[84:85], v[80:83], off nt
	s_nop 1
	v_fmamk_f32 v80, v249, 0x3a800000, v169
	v_cmp_gt_f32_e32 vcc, s58, v80
	v_mul_f32_e32 v81, 0x4b800000, v80
	s_nop 0
	v_cndmask_b32_e32 v80, v80, v81, vcc
	v_rsq_f32_e32 v80, v80
	s_nop 0
	v_mul_f32_e32 v81, 0x45800000, v80
	v_cndmask_b32_e32 v80, v80, v81, vcc
	v_pk_mul_f32 v[76:77], v[76:77], v[80:81] op_sel_hi:[1,0]
	s_nop 0
	v_mul_f32_e32 v81, 0xbfb8aa3b, v76
	v_exp_f32_e32 v81, v81
	s_nop 0
	v_add_f32_e32 v81, 1.0, v81
	v_rcp_f32_e32 v82, v81
	v_pk_mul_f32 v[68:69], v[68:69], v[80:81] op_sel_hi:[1,0]
	v_mul_f32_e32 v81, 0xbfb8aa3b, v77
	v_exp_f32_e32 v81, v81
	s_nop 0
	v_add_f32_e32 v81, 1.0, v81
	v_rcp_f32_e32 v83, v81
	v_pk_mul_f32 v[70:71], v[70:71], v[80:81] op_sel_hi:[1,0]
	v_pk_mul_f32 v[72:73], v[72:73], v[80:81] op_sel_hi:[1,0]
	v_pk_mul_f32 v[64:65], v[64:65], v[80:81] op_sel_hi:[1,0]
	v_pk_mul_f32 v[76:77], v[76:77], v[82:83]
	v_pk_mul_f32 v[66:67], v[66:67], v[80:81] op_sel_hi:[1,0]
	v_pk_mul_f32 v[68:69], v[68:69], v[76:77]
	v_pk_mul_f32 v[76:77], v[78:79], v[80:81] op_sel_hi:[1,0]
	s_nop 0
	v_mul_f32_e32 v78, 0xbfb8aa3b, v76
	v_mul_f32_e32 v79, 0xbfb8aa3b, v77
	v_exp_f32_e32 v78, v78
	v_exp_f32_e32 v79, v79
	v_add_f32_e32 v78, 1.0, v78
	v_add_f32_e32 v79, 1.0, v79
	v_rcp_f32_e32 v78, v78
	v_rcp_f32_e32 v79, v79
	s_nop 0
	v_pk_mul_f32 v[76:77], v[76:77], v[78:79]
	s_nop 0
	v_pk_mul_f32 v[70:71], v[70:71], v[76:77]
	v_mul_f32_e32 v76, 0xbfb8aa3b, v72
	v_mul_f32_e32 v77, 0xbfb8aa3b, v73
	v_exp_f32_e32 v76, v76
	v_exp_f32_e32 v77, v77
	v_add_f32_e32 v76, 1.0, v76
	v_add_f32_e32 v77, 1.0, v77
	v_rcp_f32_e32 v76, v76
	v_rcp_f32_e32 v77, v77
	s_nop 0
	v_pk_mul_f32 v[72:73], v[72:73], v[76:77]
	s_nop 0
	v_pk_mul_f32 v[72:73], v[64:65], v[72:73]
	v_pk_mul_f32 v[64:65], v[74:75], v[80:81] op_sel_hi:[1,0]
	s_nop 0
	v_mul_f32_e32 v74, 0xbfb8aa3b, v64
	v_mul_f32_e32 v75, 0xbfb8aa3b, v65
	v_exp_f32_e32 v74, v74
	v_exp_f32_e32 v75, v75
	v_add_f32_e32 v74, 1.0, v74
	v_add_f32_e32 v75, 1.0, v75
	v_rcp_f32_e32 v74, v74
	v_rcp_f32_e32 v75, v75
	s_nop 0
	v_pk_mul_f32 v[64:65], v[64:65], v[74:75]
	s_nop 0
	v_pk_mul_f32 v[74:75], v[66:67], v[64:65]
	v_cvt_pk_bf16_f32 v64, v68, v69
	v_lshl_add_u64 v[68:69], s[14:15], 0, v[146:147]
	v_cvt_pk_bf16_f32 v65, v70, v71
	v_cvt_pk_bf16_f32 v66, v72, v73
	v_cvt_pk_bf16_f32 v67, v74, v75
	v_lshl_add_u64 v[68:69], v[68:69], 0, v[136:137]
	global_store_dwordx4 v[68:69], v[64:67], off nt
	s_nop 1
	v_fmamk_f32 v64, v250, 0x3a800000, v169
	v_cmp_gt_f32_e32 vcc, s58, v64
	v_mul_f32_e32 v65, 0x4b800000, v64
	s_nop 0
	v_cndmask_b32_e32 v64, v64, v65, vcc
	v_rsq_f32_e32 v64, v64
	s_nop 0
	v_mul_f32_e32 v65, 0x45800000, v64
	v_cndmask_b32_e32 v64, v64, v65, vcc
	v_pk_mul_f32 v[60:61], v[60:61], v[64:65] op_sel_hi:[1,0]
	s_nop 0
	v_mul_f32_e32 v65, 0xbfb8aa3b, v60
	v_exp_f32_e32 v65, v65
	s_nop 0
	v_add_f32_e32 v65, 1.0, v65
	v_rcp_f32_e32 v66, v65
	v_pk_mul_f32 v[52:53], v[52:53], v[64:65] op_sel_hi:[1,0]
	v_mul_f32_e32 v65, 0xbfb8aa3b, v61
	v_exp_f32_e32 v65, v65
	s_nop 0
	v_add_f32_e32 v65, 1.0, v65
	v_rcp_f32_e32 v67, v65
	v_pk_mul_f32 v[54:55], v[54:55], v[64:65] op_sel_hi:[1,0]
	v_pk_mul_f32 v[56:57], v[56:57], v[64:65] op_sel_hi:[1,0]
	v_pk_mul_f32 v[48:49], v[48:49], v[64:65] op_sel_hi:[1,0]
	v_pk_mul_f32 v[60:61], v[60:61], v[66:67]
	v_pk_mul_f32 v[50:51], v[50:51], v[64:65] op_sel_hi:[1,0]
	v_pk_mul_f32 v[52:53], v[52:53], v[60:61]
	v_pk_mul_f32 v[60:61], v[62:63], v[64:65] op_sel_hi:[1,0]
	s_nop 0
	v_mul_f32_e32 v62, 0xbfb8aa3b, v60
	v_mul_f32_e32 v63, 0xbfb8aa3b, v61
	v_exp_f32_e32 v62, v62
	v_exp_f32_e32 v63, v63
	v_add_f32_e32 v62, 1.0, v62
	v_add_f32_e32 v63, 1.0, v63
	v_rcp_f32_e32 v62, v62
	v_rcp_f32_e32 v63, v63
	s_nop 0
	v_pk_mul_f32 v[60:61], v[60:61], v[62:63]
	s_nop 0
	v_pk_mul_f32 v[54:55], v[54:55], v[60:61]
	v_mul_f32_e32 v60, 0xbfb8aa3b, v56
	v_mul_f32_e32 v61, 0xbfb8aa3b, v57
	v_exp_f32_e32 v60, v60
	v_exp_f32_e32 v61, v61
	v_add_f32_e32 v60, 1.0, v60
	v_add_f32_e32 v61, 1.0, v61
	v_rcp_f32_e32 v60, v60
	v_rcp_f32_e32 v61, v61
	s_nop 0
	v_pk_mul_f32 v[56:57], v[56:57], v[60:61]
	s_nop 0
	v_pk_mul_f32 v[56:57], v[48:49], v[56:57]
	v_pk_mul_f32 v[48:49], v[58:59], v[64:65] op_sel_hi:[1,0]
	s_nop 0
	v_mul_f32_e32 v58, 0xbfb8aa3b, v48
	v_mul_f32_e32 v59, 0xbfb8aa3b, v49
	v_exp_f32_e32 v58, v58
	v_exp_f32_e32 v59, v59
	v_add_f32_e32 v58, 1.0, v58
	v_add_f32_e32 v59, 1.0, v59
	v_rcp_f32_e32 v58, v58
	v_rcp_f32_e32 v59, v59
	s_nop 0
	v_pk_mul_f32 v[48:49], v[48:49], v[58:59]
	s_nop 0
	v_pk_mul_f32 v[58:59], v[50:51], v[48:49]
	v_cvt_pk_bf16_f32 v48, v52, v53
	v_lshl_add_u64 v[52:53], s[14:15], 0, v[148:149]
	v_cvt_pk_bf16_f32 v49, v54, v55
	v_cvt_pk_bf16_f32 v50, v56, v57
	v_cvt_pk_bf16_f32 v51, v58, v59
	v_lshl_add_u64 v[52:53], v[52:53], 0, v[136:137]
	global_store_dwordx4 v[52:53], v[48:51], off nt
	s_nop 1
	v_fmamk_f32 v48, v251, 0x3a800000, v169
	v_cmp_gt_f32_e32 vcc, s58, v48
	v_mul_f32_e32 v49, 0x4b800000, v48
	s_nop 0
	v_cndmask_b32_e32 v48, v48, v49, vcc
	v_rsq_f32_e32 v48, v48
	s_nop 0
	v_mul_f32_e32 v49, 0x45800000, v48
	v_cndmask_b32_e32 v48, v48, v49, vcc
	v_pk_mul_f32 v[44:45], v[44:45], v[48:49] op_sel_hi:[1,0]
	s_nop 0
	v_mul_f32_e32 v49, 0xbfb8aa3b, v44
	v_exp_f32_e32 v49, v49
	s_nop 0
	v_add_f32_e32 v49, 1.0, v49
	v_rcp_f32_e32 v50, v49
	v_pk_mul_f32 v[36:37], v[36:37], v[48:49] op_sel_hi:[1,0]
	v_mul_f32_e32 v49, 0xbfb8aa3b, v45
	v_exp_f32_e32 v49, v49
	s_nop 0
	v_add_f32_e32 v49, 1.0, v49
	v_rcp_f32_e32 v51, v49
	v_pk_mul_f32 v[38:39], v[38:39], v[48:49] op_sel_hi:[1,0]
	v_pk_mul_f32 v[40:41], v[40:41], v[48:49] op_sel_hi:[1,0]
	v_pk_mul_f32 v[32:33], v[32:33], v[48:49] op_sel_hi:[1,0]
	v_pk_mul_f32 v[44:45], v[44:45], v[50:51]
	v_pk_mul_f32 v[34:35], v[34:35], v[48:49] op_sel_hi:[1,0]
	v_pk_mul_f32 v[36:37], v[36:37], v[44:45]
	v_pk_mul_f32 v[44:45], v[46:47], v[48:49] op_sel_hi:[1,0]
	s_nop 0
	v_mul_f32_e32 v46, 0xbfb8aa3b, v44
	v_mul_f32_e32 v47, 0xbfb8aa3b, v45
	v_exp_f32_e32 v46, v46
	v_exp_f32_e32 v47, v47
	v_add_f32_e32 v46, 1.0, v46
	v_add_f32_e32 v47, 1.0, v47
	v_rcp_f32_e32 v46, v46
	v_rcp_f32_e32 v47, v47
	s_nop 0
	v_pk_mul_f32 v[44:45], v[44:45], v[46:47]
	s_nop 0
	v_pk_mul_f32 v[38:39], v[38:39], v[44:45]
	v_mul_f32_e32 v44, 0xbfb8aa3b, v40
	v_mul_f32_e32 v45, 0xbfb8aa3b, v41
	v_exp_f32_e32 v44, v44
	v_exp_f32_e32 v45, v45
	v_add_f32_e32 v44, 1.0, v44
	v_add_f32_e32 v45, 1.0, v45
	v_rcp_f32_e32 v44, v44
	v_rcp_f32_e32 v45, v45
	s_nop 0
	v_pk_mul_f32 v[40:41], v[40:41], v[44:45]
	s_nop 0
	v_pk_mul_f32 v[40:41], v[32:33], v[40:41]
	v_pk_mul_f32 v[32:33], v[42:43], v[48:49] op_sel_hi:[1,0]
	s_nop 0
	v_mul_f32_e32 v42, 0xbfb8aa3b, v32
	v_mul_f32_e32 v43, 0xbfb8aa3b, v33
	v_exp_f32_e32 v42, v42
	v_exp_f32_e32 v43, v43
	v_add_f32_e32 v42, 1.0, v42
	v_add_f32_e32 v43, 1.0, v43
	v_rcp_f32_e32 v42, v42
	v_rcp_f32_e32 v43, v43
	s_nop 0
	v_pk_mul_f32 v[32:33], v[32:33], v[42:43]
	s_nop 0
	v_pk_mul_f32 v[42:43], v[34:35], v[32:33]
	v_cvt_pk_bf16_f32 v32, v36, v37
	v_lshl_add_u64 v[36:37], s[14:15], 0, v[150:151]
	v_cvt_pk_bf16_f32 v33, v38, v39
	v_cvt_pk_bf16_f32 v34, v40, v41
	v_cvt_pk_bf16_f32 v35, v42, v43
	v_lshl_add_u64 v[36:37], v[36:37], 0, v[136:137]
	global_store_dwordx4 v[36:37], v[32:35], off nt
	s_nop 1
	v_fmamk_f32 v32, v252, 0x3a800000, v169
	v_cmp_gt_f32_e32 vcc, s58, v32
	v_mul_f32_e32 v33, 0x4b800000, v32
	s_nop 0
	v_cndmask_b32_e32 v32, v32, v33, vcc
	v_rsq_f32_e32 v32, v32
	s_nop 0
	v_mul_f32_e32 v33, 0x45800000, v32
	v_cndmask_b32_e32 v32, v32, v33, vcc
	v_pk_mul_f32 v[28:29], v[28:29], v[32:33] op_sel_hi:[1,0]
	s_nop 0
	v_mul_f32_e32 v33, 0xbfb8aa3b, v28
	v_exp_f32_e32 v33, v33
	s_nop 0
	v_add_f32_e32 v33, 1.0, v33
	v_rcp_f32_e32 v34, v33
	v_pk_mul_f32 v[20:21], v[20:21], v[32:33] op_sel_hi:[1,0]
	v_mul_f32_e32 v33, 0xbfb8aa3b, v29
	v_exp_f32_e32 v33, v33
	s_nop 0
	v_add_f32_e32 v33, 1.0, v33
	v_rcp_f32_e32 v35, v33
	v_pk_mul_f32 v[22:23], v[22:23], v[32:33] op_sel_hi:[1,0]
	v_pk_mul_f32 v[24:25], v[24:25], v[32:33] op_sel_hi:[1,0]
	v_pk_mul_f32 v[16:17], v[16:17], v[32:33] op_sel_hi:[1,0]
	v_pk_mul_f32 v[28:29], v[28:29], v[34:35]
	v_pk_mul_f32 v[18:19], v[18:19], v[32:33] op_sel_hi:[1,0]
	v_pk_mul_f32 v[20:21], v[20:21], v[28:29]
	v_pk_mul_f32 v[28:29], v[30:31], v[32:33] op_sel_hi:[1,0]
	s_nop 0
	v_mul_f32_e32 v30, 0xbfb8aa3b, v28
	v_mul_f32_e32 v31, 0xbfb8aa3b, v29
	v_exp_f32_e32 v30, v30
	v_exp_f32_e32 v31, v31
	v_add_f32_e32 v30, 1.0, v30
	v_add_f32_e32 v31, 1.0, v31
	v_rcp_f32_e32 v30, v30
	v_rcp_f32_e32 v31, v31
	s_nop 0
	v_pk_mul_f32 v[28:29], v[28:29], v[30:31]
	s_nop 0
	v_pk_mul_f32 v[22:23], v[22:23], v[28:29]
	v_mul_f32_e32 v28, 0xbfb8aa3b, v24
	v_mul_f32_e32 v29, 0xbfb8aa3b, v25
	v_exp_f32_e32 v28, v28
	v_exp_f32_e32 v29, v29
	v_add_f32_e32 v28, 1.0, v28
	v_add_f32_e32 v29, 1.0, v29
	v_rcp_f32_e32 v28, v28
	v_rcp_f32_e32 v29, v29
	s_nop 0
	v_pk_mul_f32 v[24:25], v[24:25], v[28:29]
	s_nop 0
	v_pk_mul_f32 v[24:25], v[16:17], v[24:25]
	v_pk_mul_f32 v[16:17], v[26:27], v[32:33] op_sel_hi:[1,0]
	s_nop 0
	v_mul_f32_e32 v26, 0xbfb8aa3b, v16
	v_mul_f32_e32 v27, 0xbfb8aa3b, v17
	v_exp_f32_e32 v26, v26
	v_exp_f32_e32 v27, v27
	v_add_f32_e32 v26, 1.0, v26
	v_add_f32_e32 v27, 1.0, v27
	v_rcp_f32_e32 v26, v26
	v_rcp_f32_e32 v27, v27
	s_nop 0
	v_pk_mul_f32 v[16:17], v[16:17], v[26:27]
	s_nop 0
	v_pk_mul_f32 v[26:27], v[18:19], v[16:17]
	v_cvt_pk_bf16_f32 v16, v20, v21
	v_lshl_add_u64 v[20:21], s[14:15], 0, v[152:153]
	v_cvt_pk_bf16_f32 v17, v22, v23
	v_cvt_pk_bf16_f32 v18, v24, v25
	v_cvt_pk_bf16_f32 v19, v26, v27
	v_lshl_add_u64 v[20:21], v[20:21], 0, v[136:137]
	global_store_dwordx4 v[20:21], v[16:19], off nt
	s_nop 1
	v_fmamk_f32 v16, v253, 0x3a800000, v169
	v_cmp_gt_f32_e32 vcc, s58, v16
	v_mul_f32_e32 v17, 0x4b800000, v16
	s_nop 0
	v_cndmask_b32_e32 v16, v16, v17, vcc
	v_rsq_f32_e32 v16, v16
	s_nop 0
	v_mul_f32_e32 v17, 0x45800000, v16
	v_cndmask_b32_e32 v16, v16, v17, vcc
	v_pk_mul_f32 v[12:13], v[12:13], v[16:17] op_sel_hi:[1,0]
	s_andn2_b64 vcc, exec, s[2:3]
	v_mul_f32_e32 v17, 0xbfb8aa3b, v12
	v_exp_f32_e32 v17, v17
	s_nop 0
	v_add_f32_e32 v17, 1.0, v17
	v_rcp_f32_e32 v18, v17
	v_pk_mul_f32 v[4:5], v[4:5], v[16:17] op_sel_hi:[1,0]
	v_mul_f32_e32 v17, 0xbfb8aa3b, v13
	v_exp_f32_e32 v17, v17
	s_nop 0
	v_add_f32_e32 v17, 1.0, v17
	v_rcp_f32_e32 v19, v17
	v_pk_mul_f32 v[6:7], v[6:7], v[16:17] op_sel_hi:[1,0]
	v_pk_mul_f32 v[8:9], v[8:9], v[16:17] op_sel_hi:[1,0]
	v_pk_mul_f32 v[0:1], v[0:1], v[16:17] op_sel_hi:[1,0]
	v_pk_mul_f32 v[12:13], v[12:13], v[18:19]
	v_pk_mul_f32 v[2:3], v[2:3], v[16:17] op_sel_hi:[1,0]
	v_pk_mul_f32 v[4:5], v[4:5], v[12:13]
	v_pk_mul_f32 v[12:13], v[14:15], v[16:17] op_sel_hi:[1,0]
	s_nop 0
	v_mul_f32_e32 v14, 0xbfb8aa3b, v12
	v_mul_f32_e32 v15, 0xbfb8aa3b, v13
	v_exp_f32_e32 v14, v14
	v_exp_f32_e32 v15, v15
	v_add_f32_e32 v14, 1.0, v14
	v_add_f32_e32 v15, 1.0, v15
	v_rcp_f32_e32 v14, v14
	v_rcp_f32_e32 v15, v15
	s_nop 0
	v_pk_mul_f32 v[12:13], v[12:13], v[14:15]
	s_nop 0
	v_pk_mul_f32 v[6:7], v[6:7], v[12:13]
	v_mul_f32_e32 v12, 0xbfb8aa3b, v8
	v_mul_f32_e32 v13, 0xbfb8aa3b, v9
	v_exp_f32_e32 v12, v12
	v_exp_f32_e32 v13, v13
	v_add_f32_e32 v12, 1.0, v12
	v_add_f32_e32 v13, 1.0, v13
	v_rcp_f32_e32 v12, v12
	v_rcp_f32_e32 v13, v13
	s_nop 0
	v_pk_mul_f32 v[8:9], v[8:9], v[12:13]
	s_nop 0
	v_pk_mul_f32 v[8:9], v[0:1], v[8:9]
	v_pk_mul_f32 v[0:1], v[10:11], v[16:17] op_sel_hi:[1,0]
	s_nop 0
	v_mul_f32_e32 v10, 0xbfb8aa3b, v0
	v_mul_f32_e32 v11, 0xbfb8aa3b, v1
	v_exp_f32_e32 v10, v10
	v_exp_f32_e32 v11, v11
	v_add_f32_e32 v10, 1.0, v10
	v_add_f32_e32 v11, 1.0, v11
	v_rcp_f32_e32 v10, v10
	v_rcp_f32_e32 v11, v11
	s_nop 0
	v_pk_mul_f32 v[0:1], v[0:1], v[10:11]
	s_nop 0
	v_pk_mul_f32 v[10:11], v[2:3], v[0:1]
	v_cvt_pk_bf16_f32 v0, v4, v5
	v_lshl_add_u64 v[4:5], s[14:15], 0, v[154:155]
	v_cvt_pk_bf16_f32 v1, v6, v7
	v_cvt_pk_bf16_f32 v2, v8, v9
	v_cvt_pk_bf16_f32 v3, v10, v11
	v_lshl_add_u64 v[4:5], v[4:5], 0, v[136:137]
	s_mov_b64 s[14:15], -1
	global_store_dwordx4 v[4:5], v[0:3], off nt
	s_cbranch_vccnz .LBB0_169
	s_andn2_b64 vcc, exec, s[0:1]
	s_cbranch_vccnz .LBB0_168
	s_barrier
	s_branch .LBB0_168

.LBB0_336:
	v_lshl_add_u32 v254, s30, 8, v148
	v_ashrrev_i32_e32 v255, 31, v254
	v_lshl_add_u64 v[254:255], v[254:255], 2, s[6:7]
	global_load_dword v246, v[254:255], off
	global_load_dword v247, v[254:255], off offset:64
	global_load_dword v248, v[254:255], off offset:128
	global_load_dword v249, v[254:255], off offset:192
	global_load_dword v250, v[254:255], off offset:512
	global_load_dword v251, v[254:255], off offset:576
	global_load_dword v252, v[254:255], off offset:640
	global_load_dword v253, v[254:255], off offset:704
	s_add_u32 s34, s34, 0x40080
	s_addc_u32 s35, s35, 0
	s_add_u32 s13, s42, 0x100
	v_mov_b32_e32 v0, 0
	s_addc_u32 s64, s43, 0
	s_mov_b32 s65, -2
	v_mov_b32_e32 v1, v0
	v_mov_b32_e32 v2, v0
	v_mov_b32_e32 v3, v0
	v_mov_b32_e32 v4, v0
	v_mov_b32_e32 v5, v0
	v_mov_b32_e32 v6, v0
	v_mov_b32_e32 v7, v0
	v_mov_b32_e32 v16, v0
	v_mov_b32_e32 v17, v0
	v_mov_b32_e32 v18, v0
	v_mov_b32_e32 v19, v0
	v_mov_b32_e32 v20, v0
	v_mov_b32_e32 v21, v0
	v_mov_b32_e32 v22, v0
	v_mov_b32_e32 v23, v0
	v_mov_b32_e32 v32, v0
	v_mov_b32_e32 v33, v0
	v_mov_b32_e32 v34, v0
	v_mov_b32_e32 v35, v0
	v_mov_b32_e32 v36, v0
	v_mov_b32_e32 v37, v0
	v_mov_b32_e32 v38, v0
	v_mov_b32_e32 v39, v0
	v_mov_b32_e32 v48, v0
	v_mov_b32_e32 v49, v0
	v_mov_b32_e32 v50, v0
	v_mov_b32_e32 v51, v0
	v_mov_b32_e32 v52, v0
	v_mov_b32_e32 v53, v0
	v_mov_b32_e32 v54, v0
	v_mov_b32_e32 v55, v0
	v_mov_b32_e32 v8, v0
	v_mov_b32_e32 v9, v0
	v_mov_b32_e32 v10, v0
	v_mov_b32_e32 v11, v0
	v_mov_b32_e32 v12, v0
	v_mov_b32_e32 v13, v0
	v_mov_b32_e32 v14, v0
	v_mov_b32_e32 v15, v0
	v_mov_b32_e32 v24, v0
	v_mov_b32_e32 v25, v0
	v_mov_b32_e32 v26, v0
	v_mov_b32_e32 v27, v0
	v_mov_b32_e32 v28, v0
	v_mov_b32_e32 v29, v0
	v_mov_b32_e32 v30, v0
	v_mov_b32_e32 v31, v0
	v_mov_b32_e32 v40, v0
	v_mov_b32_e32 v41, v0
	v_mov_b32_e32 v42, v0
	v_mov_b32_e32 v43, v0
	v_mov_b32_e32 v44, v0
	v_mov_b32_e32 v45, v0
	v_mov_b32_e32 v46, v0
	v_mov_b32_e32 v47, v0
	v_mov_b32_e32 v56, v0
	v_mov_b32_e32 v57, v0
	v_mov_b32_e32 v58, v0
	v_mov_b32_e32 v59, v0
	v_mov_b32_e32 v60, v0
	v_mov_b32_e32 v61, v0
	v_mov_b32_e32 v62, v0
	v_mov_b32_e32 v63, v0
	v_mov_b32_e32 v64, v0
	v_mov_b32_e32 v65, v0
	v_mov_b32_e32 v66, v0
	v_mov_b32_e32 v67, v0
	v_mov_b32_e32 v68, v0
	v_mov_b32_e32 v69, v0
	v_mov_b32_e32 v70, v0
	v_mov_b32_e32 v71, v0
	v_mov_b32_e32 v80, v0
	v_mov_b32_e32 v81, v0
	v_mov_b32_e32 v82, v0
	v_mov_b32_e32 v83, v0
	v_mov_b32_e32 v84, v0
	v_mov_b32_e32 v85, v0
	v_mov_b32_e32 v86, v0
	v_mov_b32_e32 v87, v0
	v_mov_b32_e32 v96, v0
	v_mov_b32_e32 v97, v0
	v_mov_b32_e32 v98, v0
	v_mov_b32_e32 v99, v0
	v_mov_b32_e32 v100, v0
	v_mov_b32_e32 v101, v0
	v_mov_b32_e32 v102, v0
	v_mov_b32_e32 v103, v0
	v_mov_b32_e32 v112, v0
	v_mov_b32_e32 v113, v0
	v_mov_b32_e32 v114, v0
	v_mov_b32_e32 v115, v0
	v_mov_b32_e32 v116, v0
	v_mov_b32_e32 v117, v0
	v_mov_b32_e32 v118, v0
	v_mov_b32_e32 v119, v0
	v_mov_b32_e32 v72, v0
	v_mov_b32_e32 v73, v0
	v_mov_b32_e32 v74, v0
	v_mov_b32_e32 v75, v0
	v_mov_b32_e32 v76, v0
	v_mov_b32_e32 v77, v0
	v_mov_b32_e32 v78, v0
	v_mov_b32_e32 v79, v0
	v_mov_b32_e32 v88, v0
	v_mov_b32_e32 v89, v0
	v_mov_b32_e32 v90, v0
	v_mov_b32_e32 v91, v0
	v_mov_b32_e32 v92, v0
	v_mov_b32_e32 v93, v0
	v_mov_b32_e32 v94, v0
	v_mov_b32_e32 v95, v0
	v_mov_b32_e32 v104, v0
	v_mov_b32_e32 v105, v0
	v_mov_b32_e32 v106, v0
	v_mov_b32_e32 v107, v0
	v_mov_b32_e32 v108, v0
	v_mov_b32_e32 v109, v0
	v_mov_b32_e32 v110, v0
	v_mov_b32_e32 v111, v0
	v_mov_b32_e32 v120, v0
	v_mov_b32_e32 v121, v0
	v_mov_b32_e32 v122, v0
	v_mov_b32_e32 v123, v0
	v_mov_b32_e32 v124, v0
	v_mov_b32_e32 v125, v0
	v_mov_b32_e32 v126, v0
	v_mov_b32_e32 v127, v0

.LBB0_340:
	v_lshl_add_u32 v146, s30, 8, v148
	v_ashrrev_i32_e32 v147, 31, v146
	v_lshl_add_u64 v[154:155], v[146:147], 2, s[6:7]
	s_lshl_b32 s30, s31, 8
	s_ashr_i32 s31, s30, 31
	s_lshl_b64 s[30:31], s[30:31], 1
	s_waitcnt vmcnt(30)
	v_fmamk_f32 v147, v246, 0x3a800000, v153
	v_cmp_gt_f32_e32 vcc, s60, v147
	v_mul_f32_e32 v154, 0x4b800000, v147
	s_nop 0
	v_cndmask_b32_e32 v147, v147, v154, vcc
	v_rsq_f32_e32 v147, v147
	s_nop 0
	v_mul_f32_e32 v154, 0x45800000, v147
	v_cndmask_b32_e32 v154, v147, v154, vcc
	v_pk_mul_f32 v[124:125], v[124:125], v[154:155] op_sel_hi:[1,0]
	v_pk_mul_f32 v[120:121], v[120:121], v[154:155] op_sel_hi:[1,0]
	v_pk_mul_f32 v[126:127], v[126:127], v[154:155] op_sel_hi:[1,0]
	v_pk_mul_f32 v[156:157], v[122:123], v[154:155] op_sel_hi:[1,0]
	v_cvt_pk_bf16_f32 v122, v124, v125
	v_cvt_pk_bf16_f32 v124, v120, v121
	v_mov_b64_e32 v[120:121], s[80:81]
	v_cvt_pk_bf16_f32 v123, v126, v127
	v_mad_i64_i32 v[126:127], s[34:35], v146, s61, v[120:121]
	v_lshl_add_u64 v[126:127], v[126:127], 0, s[30:31]
	v_lshl_add_u64 v[126:127], v[126:127], 0, s[0:1]
	v_cvt_pk_bf16_f32 v125, v156, v157
	v_lshl_add_u64 v[126:127], v[126:127], 0, v[136:137]
	global_store_dwordx4 v[126:127], v[122:125], off nt
	v_pk_mul_f32 v[118:119], v[118:119], v[154:155] op_sel_hi:[1,0]
	v_pk_mul_f32 v[116:117], v[116:117], v[154:155] op_sel_hi:[1,0]
	v_pk_mul_f32 v[122:123], v[114:115], v[154:155] op_sel_hi:[1,0]
	v_pk_mul_f32 v[114:115], v[112:113], v[154:155] op_sel_hi:[1,0]
	v_cvt_pk_bf16_f32 v112, v116, v117
	v_cvt_pk_bf16_f32 v113, v118, v119
	v_cvt_pk_bf16_f32 v114, v114, v115
	v_cvt_pk_bf16_f32 v115, v122, v123
	global_store_dwordx4 v[126:127], v[112:115], off offset:256 nt
	s_nop 1
	v_or_b32_e32 v112, 16, v146
	v_ashrrev_i32_e32 v113, 31, v112
	v_lshl_add_u64 v[114:115], v[112:113], 2, s[6:7]
	s_nop 1
	v_fmamk_f32 v113, v247, 0x3a800000, v153
	v_cmp_gt_f32_e32 vcc, s60, v113
	v_mul_f32_e32 v114, 0x4b800000, v113
	s_nop 0
	v_cndmask_b32_e32 v113, v113, v114, vcc
	v_rsq_f32_e32 v113, v113
	s_nop 0
	v_mul_f32_e32 v114, 0x45800000, v113
	v_cndmask_b32_e32 v114, v113, v114, vcc
	v_pk_mul_f32 v[108:109], v[108:109], v[114:115] op_sel_hi:[1,0]
	v_pk_mul_f32 v[116:117], v[106:107], v[114:115] op_sel_hi:[1,0]
	v_pk_mul_f32 v[106:107], v[104:105], v[114:115] op_sel_hi:[1,0]
	v_cvt_pk_bf16_f32 v104, v108, v109
	v_mad_i64_i32 v[108:109], s[34:35], v112, s61, v[120:121]
	v_lshl_add_u64 v[108:109], v[108:109], 0, s[30:31]
	v_pk_mul_f32 v[110:111], v[110:111], v[114:115] op_sel_hi:[1,0]
	v_lshl_add_u64 v[108:109], v[108:109], 0, s[0:1]
	v_cvt_pk_bf16_f32 v105, v110, v111
	v_cvt_pk_bf16_f32 v106, v106, v107
	v_cvt_pk_bf16_f32 v107, v116, v117
	v_lshl_add_u64 v[108:109], v[108:109], 0, v[136:137]
	global_store_dwordx4 v[108:109], v[104:107], off nt
	v_pk_mul_f32 v[102:103], v[102:103], v[114:115] op_sel_hi:[1,0]
	v_pk_mul_f32 v[100:101], v[100:101], v[114:115] op_sel_hi:[1,0]
	v_pk_mul_f32 v[104:105], v[98:99], v[114:115] op_sel_hi:[1,0]
	v_pk_mul_f32 v[98:99], v[96:97], v[114:115] op_sel_hi:[1,0]
	v_cvt_pk_bf16_f32 v96, v100, v101
	v_cvt_pk_bf16_f32 v97, v102, v103
	v_cvt_pk_bf16_f32 v98, v98, v99
	v_cvt_pk_bf16_f32 v99, v104, v105
	global_store_dwordx4 v[108:109], v[96:99], off offset:256 nt
	s_nop 1
	v_or_b32_e32 v96, 32, v146
	v_ashrrev_i32_e32 v97, 31, v96
	v_lshl_add_u64 v[98:99], v[96:97], 2, s[6:7]
	s_nop 1
	v_fmamk_f32 v97, v248, 0x3a800000, v153
	v_cmp_gt_f32_e32 vcc, s60, v97
	v_mul_f32_e32 v98, 0x4b800000, v97
	s_nop 0
	v_cndmask_b32_e32 v97, v97, v98, vcc
	v_rsq_f32_e32 v97, v97
	s_nop 0
	v_mul_f32_e32 v98, 0x45800000, v97
	v_cndmask_b32_e32 v98, v97, v98, vcc
	v_pk_mul_f32 v[92:93], v[92:93], v[98:99] op_sel_hi:[1,0]
	v_pk_mul_f32 v[100:101], v[90:91], v[98:99] op_sel_hi:[1,0]
	v_pk_mul_f32 v[90:91], v[88:89], v[98:99] op_sel_hi:[1,0]
	v_cvt_pk_bf16_f32 v88, v92, v93
	v_mad_i64_i32 v[92:93], s[34:35], v96, s61, v[120:121]
	v_lshl_add_u64 v[92:93], v[92:93], 0, s[30:31]
	v_pk_mul_f32 v[94:95], v[94:95], v[98:99] op_sel_hi:[1,0]
	v_lshl_add_u64 v[92:93], v[92:93], 0, s[0:1]
	v_cvt_pk_bf16_f32 v89, v94, v95
	v_cvt_pk_bf16_f32 v90, v90, v91
	v_cvt_pk_bf16_f32 v91, v100, v101
	v_lshl_add_u64 v[92:93], v[92:93], 0, v[136:137]
	global_store_dwordx4 v[92:93], v[88:91], off nt
	v_pk_mul_f32 v[86:87], v[86:87], v[98:99] op_sel_hi:[1,0]
	v_pk_mul_f32 v[84:85], v[84:85], v[98:99] op_sel_hi:[1,0]
	v_pk_mul_f32 v[88:89], v[82:83], v[98:99] op_sel_hi:[1,0]
	v_pk_mul_f32 v[82:83], v[80:81], v[98:99] op_sel_hi:[1,0]
	v_cvt_pk_bf16_f32 v80, v84, v85
	v_cvt_pk_bf16_f32 v81, v86, v87
	v_cvt_pk_bf16_f32 v82, v82, v83
	v_cvt_pk_bf16_f32 v83, v88, v89
	global_store_dwordx4 v[92:93], v[80:83], off offset:256 nt
	s_nop 1
	v_or_b32_e32 v80, 48, v146
	v_ashrrev_i32_e32 v81, 31, v80
	v_lshl_add_u64 v[82:83], v[80:81], 2, s[6:7]
	s_nop 1
	v_fmamk_f32 v81, v249, 0x3a800000, v153
	v_cmp_gt_f32_e32 vcc, s60, v81
	v_mul_f32_e32 v82, 0x4b800000, v81
	s_nop 0
	v_cndmask_b32_e32 v81, v81, v82, vcc
	v_rsq_f32_e32 v81, v81
	s_nop 0
	v_mul_f32_e32 v82, 0x45800000, v81
	v_cndmask_b32_e32 v82, v81, v82, vcc
	v_pk_mul_f32 v[76:77], v[76:77], v[82:83] op_sel_hi:[1,0]
	v_pk_mul_f32 v[84:85], v[74:75], v[82:83] op_sel_hi:[1,0]
	v_pk_mul_f32 v[74:75], v[72:73], v[82:83] op_sel_hi:[1,0]
	v_cvt_pk_bf16_f32 v72, v76, v77
	v_mad_i64_i32 v[76:77], s[34:35], v80, s61, v[120:121]
	v_lshl_add_u64 v[76:77], v[76:77], 0, s[30:31]
	v_pk_mul_f32 v[78:79], v[78:79], v[82:83] op_sel_hi:[1,0]
	v_lshl_add_u64 v[76:77], v[76:77], 0, s[0:1]
	v_cvt_pk_bf16_f32 v73, v78, v79
	v_cvt_pk_bf16_f32 v74, v74, v75
	v_cvt_pk_bf16_f32 v75, v84, v85
	v_lshl_add_u64 v[76:77], v[76:77], 0, v[136:137]
	global_store_dwordx4 v[76:77], v[72:75], off nt
	v_pk_mul_f32 v[70:71], v[70:71], v[82:83] op_sel_hi:[1,0]
	v_pk_mul_f32 v[68:69], v[68:69], v[82:83] op_sel_hi:[1,0]
	v_pk_mul_f32 v[72:73], v[66:67], v[82:83] op_sel_hi:[1,0]
	v_pk_mul_f32 v[66:67], v[64:65], v[82:83] op_sel_hi:[1,0]
	v_cvt_pk_bf16_f32 v64, v68, v69
	v_cvt_pk_bf16_f32 v65, v70, v71
	v_cvt_pk_bf16_f32 v66, v66, v67
	v_cvt_pk_bf16_f32 v67, v72, v73
	global_store_dwordx4 v[76:77], v[64:67], off offset:256 nt
	s_nop 1
	v_add_u32_e32 v64, 0x80, v146
	v_ashrrev_i32_e32 v65, 31, v64
	v_lshl_add_u64 v[66:67], v[64:65], 2, s[6:7]
	s_nop 1
	v_fmamk_f32 v65, v250, 0x3a800000, v153
	v_cmp_gt_f32_e32 vcc, s60, v65
	v_mul_f32_e32 v66, 0x4b800000, v65
	s_nop 0
	v_cndmask_b32_e32 v65, v65, v66, vcc
	v_rsq_f32_e32 v65, v65
	s_nop 0
	v_mul_f32_e32 v66, 0x45800000, v65
	v_cndmask_b32_e32 v66, v65, v66, vcc
	v_pk_mul_f32 v[60:61], v[60:61], v[66:67] op_sel_hi:[1,0]
	v_pk_mul_f32 v[68:69], v[58:59], v[66:67] op_sel_hi:[1,0]
	v_pk_mul_f32 v[58:59], v[56:57], v[66:67] op_sel_hi:[1,0]
	v_cvt_pk_bf16_f32 v56, v60, v61
	v_mad_i64_i32 v[60:61], s[34:35], v64, s61, v[120:121]
	v_lshl_add_u64 v[60:61], v[60:61], 0, s[30:31]
	v_pk_mul_f32 v[62:63], v[62:63], v[66:67] op_sel_hi:[1,0]
	v_lshl_add_u64 v[60:61], v[60:61], 0, s[0:1]
	v_cvt_pk_bf16_f32 v57, v62, v63
	v_cvt_pk_bf16_f32 v58, v58, v59
	v_cvt_pk_bf16_f32 v59, v68, v69
	v_lshl_add_u64 v[60:61], v[60:61], 0, v[136:137]
	global_store_dwordx4 v[60:61], v[56:59], off nt
	v_pk_mul_f32 v[54:55], v[54:55], v[66:67] op_sel_hi:[1,0]
	v_pk_mul_f32 v[52:53], v[52:53], v[66:67] op_sel_hi:[1,0]
	v_pk_mul_f32 v[56:57], v[50:51], v[66:67] op_sel_hi:[1,0]
	v_pk_mul_f32 v[50:51], v[48:49], v[66:67] op_sel_hi:[1,0]
	v_cvt_pk_bf16_f32 v48, v52, v53
	v_cvt_pk_bf16_f32 v49, v54, v55
	v_cvt_pk_bf16_f32 v50, v50, v51
	v_cvt_pk_bf16_f32 v51, v56, v57
	global_store_dwordx4 v[60:61], v[48:51], off offset:256 nt
	s_nop 1
	v_add_u32_e32 v48, 0x90, v146
	v_ashrrev_i32_e32 v49, 31, v48
	v_lshl_add_u64 v[50:51], v[48:49], 2, s[6:7]
	s_nop 1
	v_fmamk_f32 v49, v251, 0x3a800000, v153
	v_cmp_gt_f32_e32 vcc, s60, v49
	v_mul_f32_e32 v50, 0x4b800000, v49
	s_nop 0
	v_cndmask_b32_e32 v49, v49, v50, vcc
	v_rsq_f32_e32 v49, v49
	s_nop 0
	v_mul_f32_e32 v50, 0x45800000, v49
	v_cndmask_b32_e32 v50, v49, v50, vcc
	v_pk_mul_f32 v[44:45], v[44:45], v[50:51] op_sel_hi:[1,0]
	v_pk_mul_f32 v[52:53], v[42:43], v[50:51] op_sel_hi:[1,0]
	v_pk_mul_f32 v[42:43], v[40:41], v[50:51] op_sel_hi:[1,0]
	v_cvt_pk_bf16_f32 v40, v44, v45
	v_mad_i64_i32 v[44:45], s[34:35], v48, s61, v[120:121]
	v_lshl_add_u64 v[44:45], v[44:45], 0, s[30:31]
	v_pk_mul_f32 v[46:47], v[46:47], v[50:51] op_sel_hi:[1,0]
	v_lshl_add_u64 v[44:45], v[44:45], 0, s[0:1]
	v_cvt_pk_bf16_f32 v41, v46, v47
	v_cvt_pk_bf16_f32 v42, v42, v43
	v_cvt_pk_bf16_f32 v43, v52, v53
	v_lshl_add_u64 v[44:45], v[44:45], 0, v[136:137]
	global_store_dwordx4 v[44:45], v[40:43], off nt
	v_pk_mul_f32 v[38:39], v[38:39], v[50:51] op_sel_hi:[1,0]
	v_pk_mul_f32 v[36:37], v[36:37], v[50:51] op_sel_hi:[1,0]
	v_pk_mul_f32 v[40:41], v[34:35], v[50:51] op_sel_hi:[1,0]
	v_pk_mul_f32 v[34:35], v[32:33], v[50:51] op_sel_hi:[1,0]
	v_cvt_pk_bf16_f32 v32, v36, v37
	v_cvt_pk_bf16_f32 v33, v38, v39
	v_cvt_pk_bf16_f32 v34, v34, v35
	v_cvt_pk_bf16_f32 v35, v40, v41
	global_store_dwordx4 v[44:45], v[32:35], off offset:256 nt
	s_nop 1
	v_add_u32_e32 v32, 0xa0, v146
	v_ashrrev_i32_e32 v33, 31, v32
	v_lshl_add_u64 v[34:35], v[32:33], 2, s[6:7]
	s_nop 1
	v_fmamk_f32 v33, v252, 0x3a800000, v153
	v_cmp_gt_f32_e32 vcc, s60, v33
	v_mul_f32_e32 v34, 0x4b800000, v33
	s_nop 0
	v_cndmask_b32_e32 v33, v33, v34, vcc
	v_rsq_f32_e32 v33, v33
	s_nop 0
	v_mul_f32_e32 v34, 0x45800000, v33
	v_cndmask_b32_e32 v34, v33, v34, vcc
	v_pk_mul_f32 v[28:29], v[28:29], v[34:35] op_sel_hi:[1,0]
	v_pk_mul_f32 v[36:37], v[26:27], v[34:35] op_sel_hi:[1,0]
	v_pk_mul_f32 v[26:27], v[24:25], v[34:35] op_sel_hi:[1,0]
	v_cvt_pk_bf16_f32 v24, v28, v29
	v_mad_i64_i32 v[28:29], s[34:35], v32, s61, v[120:121]
	v_lshl_add_u64 v[28:29], v[28:29], 0, s[30:31]
	v_pk_mul_f32 v[30:31], v[30:31], v[34:35] op_sel_hi:[1,0]
	v_lshl_add_u64 v[28:29], v[28:29], 0, s[0:1]
	v_cvt_pk_bf16_f32 v25, v30, v31
	v_cvt_pk_bf16_f32 v26, v26, v27
	v_cvt_pk_bf16_f32 v27, v36, v37
	v_lshl_add_u64 v[28:29], v[28:29], 0, v[136:137]
	global_store_dwordx4 v[28:29], v[24:27], off nt
	v_pk_mul_f32 v[22:23], v[22:23], v[34:35] op_sel_hi:[1,0]
	v_pk_mul_f32 v[20:21], v[20:21], v[34:35] op_sel_hi:[1,0]
	v_pk_mul_f32 v[24:25], v[18:19], v[34:35] op_sel_hi:[1,0]
	v_pk_mul_f32 v[18:19], v[16:17], v[34:35] op_sel_hi:[1,0]
	v_cvt_pk_bf16_f32 v16, v20, v21
	v_cvt_pk_bf16_f32 v17, v22, v23
	v_cvt_pk_bf16_f32 v18, v18, v19
	v_cvt_pk_bf16_f32 v19, v24, v25
	global_store_dwordx4 v[28:29], v[16:19], off offset:256 nt
	s_nop 1
	v_add_u32_e32 v16, 0xb0, v146
	v_ashrrev_i32_e32 v17, 31, v16
	v_lshl_add_u64 v[18:19], v[16:17], 2, s[6:7]
	s_nop 1
	v_fmamk_f32 v17, v253, 0x3a800000, v153
	v_cmp_gt_f32_e32 vcc, s60, v17
	v_mul_f32_e32 v18, 0x4b800000, v17
	s_nop 0
	v_cndmask_b32_e32 v17, v17, v18, vcc
	v_rsq_f32_e32 v17, v17
	s_nop 0
	v_mul_f32_e32 v18, 0x45800000, v17
	v_cndmask_b32_e32 v18, v17, v18, vcc
	v_pk_mul_f32 v[12:13], v[12:13], v[18:19] op_sel_hi:[1,0]
	v_pk_mul_f32 v[20:21], v[10:11], v[18:19] op_sel_hi:[1,0]
	v_pk_mul_f32 v[10:11], v[8:9], v[18:19] op_sel_hi:[1,0]
	v_cvt_pk_bf16_f32 v8, v12, v13
	v_mad_i64_i32 v[12:13], s[34:35], v16, s61, v[120:121]
	v_lshl_add_u64 v[12:13], v[12:13], 0, s[30:31]
	v_pk_mul_f32 v[14:15], v[14:15], v[18:19] op_sel_hi:[1,0]
	v_lshl_add_u64 v[12:13], v[12:13], 0, s[0:1]
	v_cvt_pk_bf16_f32 v9, v14, v15
	v_cvt_pk_bf16_f32 v10, v10, v11
	v_cvt_pk_bf16_f32 v11, v20, v21
	v_lshl_add_u64 v[12:13], v[12:13], 0, v[136:137]
	global_store_dwordx4 v[12:13], v[8:11], off nt
	v_pk_mul_f32 v[6:7], v[6:7], v[18:19] op_sel_hi:[1,0]
	v_pk_mul_f32 v[4:5], v[4:5], v[18:19] op_sel_hi:[1,0]
	v_pk_mul_f32 v[8:9], v[2:3], v[18:19] op_sel_hi:[1,0]
	v_pk_mul_f32 v[2:3], v[0:1], v[18:19] op_sel_hi:[1,0]
	v_cvt_pk_bf16_f32 v0, v4, v5
	v_cvt_pk_bf16_f32 v1, v6, v7
	v_cvt_pk_bf16_f32 v2, v2, v3
	v_cvt_pk_bf16_f32 v3, v8, v9
	s_mov_b64 s[30:31], -1
	s_andn2_b64 vcc, exec, s[2:3]
	global_store_dwordx4 v[12:13], v[0:3], off offset:256 nt
	s_cbranch_vccnz .LBB0_333
	s_andn2_b64 vcc, exec, s[4:5]
	s_cbranch_vccnz .LBB0_332
	s_barrier
	s_branch .LBB0_332

.LBB0_1626:
	v_lshl_add_u32 v254, s4, 8, v138
	v_ashrrev_i32_e32 v255, 31, v254
	v_lshl_add_u64 v[254:255], v[254:255], 2, s[6:7]
	global_load_dword v246, v[254:255], off
	global_load_dword v247, v[254:255], off offset:64
	global_load_dword v248, v[254:255], off offset:128
	global_load_dword v249, v[254:255], off offset:192
	global_load_dword v250, v[254:255], off offset:512
	global_load_dword v251, v[254:255], off offset:576
	global_load_dword v252, v[254:255], off offset:640
	global_load_dword v253, v[254:255], off offset:704
	s_add_u32 s18, s18, 0x40080
	s_addc_u32 s19, s19, 0
	s_add_u32 s13, s20, 0x100
	v_mov_b32_e32 v0, 0
	s_addc_u32 s42, s21, 0
	s_mov_b32 s43, -2
	v_mov_b32_e32 v1, v0
	v_mov_b32_e32 v2, v0
	v_mov_b32_e32 v3, v0
	v_mov_b32_e32 v4, v0
	v_mov_b32_e32 v5, v0
	v_mov_b32_e32 v6, v0
	v_mov_b32_e32 v7, v0
	s_waitcnt vmcnt(0)
	v_mov_b32_e32 v16, v0
	v_mov_b32_e32 v17, v0
	v_mov_b32_e32 v18, v0
	v_mov_b32_e32 v19, v0
	v_mov_b32_e32 v20, v0
	v_mov_b32_e32 v21, v0
	v_mov_b32_e32 v22, v0
	v_mov_b32_e32 v23, v0
	v_mov_b32_e32 v32, v0
	v_mov_b32_e32 v33, v0
	v_mov_b32_e32 v34, v0
	v_mov_b32_e32 v35, v0
	v_mov_b32_e32 v36, v0
	v_mov_b32_e32 v37, v0
	v_mov_b32_e32 v38, v0
	v_mov_b32_e32 v39, v0
	v_mov_b32_e32 v48, v0
	v_mov_b32_e32 v49, v0
	v_mov_b32_e32 v50, v0
	v_mov_b32_e32 v51, v0
	v_mov_b32_e32 v52, v0
	v_mov_b32_e32 v53, v0
	v_mov_b32_e32 v54, v0
	v_mov_b32_e32 v55, v0
	v_mov_b32_e32 v8, v0
	v_mov_b32_e32 v9, v0
	v_mov_b32_e32 v10, v0
	v_mov_b32_e32 v11, v0
	v_mov_b32_e32 v12, v0
	v_mov_b32_e32 v13, v0
	v_mov_b32_e32 v14, v0
	v_mov_b32_e32 v15, v0
	v_mov_b32_e32 v24, v0
	v_mov_b32_e32 v25, v0
	v_mov_b32_e32 v26, v0
	v_mov_b32_e32 v27, v0
	v_mov_b32_e32 v28, v0
	v_mov_b32_e32 v29, v0
	v_mov_b32_e32 v30, v0
	v_mov_b32_e32 v31, v0
	v_mov_b32_e32 v40, v0
	v_mov_b32_e32 v41, v0
	v_mov_b32_e32 v42, v0
	v_mov_b32_e32 v43, v0
	v_mov_b32_e32 v44, v0
	v_mov_b32_e32 v45, v0
	v_mov_b32_e32 v46, v0
	v_mov_b32_e32 v47, v0
	v_mov_b32_e32 v56, v0
	v_mov_b32_e32 v57, v0
	v_mov_b32_e32 v58, v0
	v_mov_b32_e32 v59, v0
	v_mov_b32_e32 v60, v0
	v_mov_b32_e32 v61, v0
	v_mov_b32_e32 v62, v0
	v_mov_b32_e32 v63, v0
	v_mov_b32_e32 v64, v0
	v_mov_b32_e32 v65, v0
	v_mov_b32_e32 v66, v0
	v_mov_b32_e32 v67, v0
	v_mov_b32_e32 v68, v0
	v_mov_b32_e32 v69, v0
	v_mov_b32_e32 v70, v0
	v_mov_b32_e32 v71, v0
	v_mov_b32_e32 v80, v0
	v_mov_b32_e32 v81, v0
	v_mov_b32_e32 v82, v0
	v_mov_b32_e32 v83, v0
	v_mov_b32_e32 v84, v0
	v_mov_b32_e32 v85, v0
	v_mov_b32_e32 v86, v0
	v_mov_b32_e32 v87, v0
	v_mov_b32_e32 v96, v0
	v_mov_b32_e32 v97, v0
	v_mov_b32_e32 v98, v0
	v_mov_b32_e32 v99, v0
	v_mov_b32_e32 v100, v0
	v_mov_b32_e32 v101, v0
	v_mov_b32_e32 v102, v0
	v_mov_b32_e32 v103, v0
	v_mov_b32_e32 v112, v0
	v_mov_b32_e32 v113, v0
	v_mov_b32_e32 v114, v0
	v_mov_b32_e32 v115, v0
	v_mov_b32_e32 v116, v0
	v_mov_b32_e32 v117, v0
	v_mov_b32_e32 v118, v0
	v_mov_b32_e32 v119, v0
	v_mov_b32_e32 v72, v0
	v_mov_b32_e32 v73, v0
	v_mov_b32_e32 v74, v0
	v_mov_b32_e32 v75, v0
	v_mov_b32_e32 v76, v0
	v_mov_b32_e32 v77, v0
	v_mov_b32_e32 v78, v0
	v_mov_b32_e32 v79, v0
	v_mov_b32_e32 v88, v0
	v_mov_b32_e32 v89, v0
	v_mov_b32_e32 v90, v0
	v_mov_b32_e32 v91, v0
	v_mov_b32_e32 v92, v0
	v_mov_b32_e32 v93, v0
	v_mov_b32_e32 v94, v0
	v_mov_b32_e32 v95, v0
	v_mov_b32_e32 v104, v0
	v_mov_b32_e32 v105, v0
	v_mov_b32_e32 v106, v0
	v_mov_b32_e32 v107, v0
	v_mov_b32_e32 v108, v0
	v_mov_b32_e32 v109, v0
	v_mov_b32_e32 v110, v0
	v_mov_b32_e32 v111, v0
	v_mov_b32_e32 v120, v0
	v_mov_b32_e32 v121, v0
	v_mov_b32_e32 v122, v0
	v_mov_b32_e32 v123, v0
	v_mov_b32_e32 v124, v0
	v_mov_b32_e32 v125, v0
	v_mov_b32_e32 v126, v0
	v_mov_b32_e32 v127, v0

.LBB0_1630:
	v_lshl_add_u32 v164, s4, 8, v138
	v_ashrrev_i32_e32 v165, 31, v164
	v_lshl_add_u64 v[166:167], v[164:165], 2, s[6:7]
	s_lshl_b32 s5, s5, 1
	s_mul_i32 s4, s4, 44
	s_add_i32 s4, s4, s5
	s_or_b32 s4, s4, s35
	s_ashr_i32 s5, s4, 31
	s_lshl_b64 s[4:5], s[4:5], 15
	s_add_u32 s18, s80, s4
	s_addc_u32 s19, s81, s5
	s_waitcnt vmcnt(30)
	v_fmamk_f32 v165, v246, 0x3a800000, v171
	v_mul_f32_e32 v172, 0x4b800000, v165
	v_cmp_gt_f32_e32 vcc, s40, v165
	s_nop 1
	v_cndmask_b32_e32 v165, v165, v172, vcc
	v_rsq_f32_e32 v165, v165
	v_lshl_add_u64 v[172:173], s[18:19], 0, v[140:141]
	v_lshl_add_u64 v[172:173], v[172:173], 0, v[136:137]
	v_mul_f32_e32 v174, 0x45800000, v165
	v_cndmask_b32_e32 v174, v165, v174, vcc
	v_pk_mul_f32 v[124:125], v[124:125], v[174:175] op_sel_hi:[1,0]
	v_pk_mul_f32 v[126:127], v[126:127], v[174:175] op_sel_hi:[1,0]
	v_pk_mul_f32 v[120:121], v[120:121], v[174:175] op_sel_hi:[1,0]
	v_pk_mul_f32 v[122:123], v[122:123], v[174:175] op_sel_hi:[1,0]
	v_pk_mul_f32 v[116:117], v[116:117], v[174:175] op_sel_hi:[1,0]
	v_pk_mul_f32 v[118:119], v[118:119], v[174:175] op_sel_hi:[1,0]
	v_pk_mul_f32 v[112:113], v[112:113], v[174:175] op_sel_hi:[1,0]
	v_pk_mul_f32 v[114:115], v[114:115], v[174:175] op_sel_hi:[1,0]
	v_mul_f32_e32 v165, 0xbfb8aa3b, v124
	v_mul_f32_e32 v174, 0xbfb8aa3b, v125
	v_mul_f32_e32 v175, 0xbfb8aa3b, v126
	v_mul_f32_e32 v176, 0xbfb8aa3b, v127
	v_mul_f32_e32 v177, 0xbfb8aa3b, v120
	v_mul_f32_e32 v178, 0xbfb8aa3b, v121
	v_mul_f32_e32 v179, 0xbfb8aa3b, v122
	v_mul_f32_e32 v180, 0xbfb8aa3b, v123
	v_exp_f32_e32 v165, v165
	v_exp_f32_e32 v174, v174
	v_exp_f32_e32 v175, v175
	v_exp_f32_e32 v176, v176
	v_exp_f32_e32 v177, v177
	v_exp_f32_e32 v178, v178
	v_exp_f32_e32 v179, v179
	v_exp_f32_e32 v180, v180
	v_add_f32_e32 v165, 1.0, v165
	v_add_f32_e32 v181, 1.0, v174
	v_add_f32_e32 v182, 1.0, v175
	v_add_f32_e32 v183, 1.0, v176
	v_add_f32_e32 v184, 1.0, v177
	v_add_f32_e32 v185, 1.0, v178
	v_add_f32_e32 v186, 1.0, v179
	v_add_f32_e32 v187, 1.0, v180
	v_rcp_f32_e32 v174, v165
	v_rcp_f32_e32 v175, v181
	v_rcp_f32_e32 v176, v182
	v_rcp_f32_e32 v177, v183
	v_rcp_f32_e32 v178, v184
	v_rcp_f32_e32 v179, v185
	v_rcp_f32_e32 v180, v186
	v_rcp_f32_e32 v181, v187
	v_pk_mul_f32 v[124:125], v[124:125], v[174:175]
	v_pk_mul_f32 v[126:127], v[126:127], v[176:177]
	v_pk_mul_f32 v[120:121], v[120:121], v[178:179]
	v_pk_mul_f32 v[122:123], v[122:123], v[180:181]
	v_pk_mul_f32 v[116:117], v[116:117], v[124:125]
	v_pk_mul_f32 v[118:119], v[118:119], v[126:127]
	v_pk_mul_f32 v[120:121], v[112:113], v[120:121]
	v_pk_mul_f32 v[122:123], v[114:115], v[122:123]
	v_cvt_pk_bf16_f32 v112, v116, v117
	v_cvt_pk_bf16_f32 v113, v118, v119
	v_cvt_pk_bf16_f32 v114, v120, v121
	v_cvt_pk_bf16_f32 v115, v122, v123
	global_store_dwordx4 v[172:173], v[112:115], off nt
	s_nop 1
	v_fmamk_f32 v112, v247, 0x3a800000, v171
	v_mul_f32_e32 v113, 0x4b800000, v112
	v_cmp_gt_f32_e32 vcc, s40, v112
	s_nop 1
	v_cndmask_b32_e32 v112, v112, v113, vcc
	v_rsq_f32_e32 v114, v112
	v_lshl_add_u64 v[112:113], s[18:19], 0, v[142:143]
	v_lshl_add_u64 v[112:113], v[112:113], 0, v[136:137]
	v_mul_f32_e32 v115, 0x45800000, v114
	v_cndmask_b32_e32 v114, v114, v115, vcc
	v_pk_mul_f32 v[108:109], v[108:109], v[114:115] op_sel_hi:[1,0]
	v_pk_mul_f32 v[110:111], v[110:111], v[114:115] op_sel_hi:[1,0]
	v_pk_mul_f32 v[104:105], v[104:105], v[114:115] op_sel_hi:[1,0]
	v_pk_mul_f32 v[106:107], v[106:107], v[114:115] op_sel_hi:[1,0]
	v_pk_mul_f32 v[100:101], v[100:101], v[114:115] op_sel_hi:[1,0]
	v_pk_mul_f32 v[102:103], v[102:103], v[114:115] op_sel_hi:[1,0]
	v_pk_mul_f32 v[96:97], v[96:97], v[114:115] op_sel_hi:[1,0]
	v_pk_mul_f32 v[98:99], v[98:99], v[114:115] op_sel_hi:[1,0]
	v_mul_f32_e32 v114, 0xbfb8aa3b, v108
	v_mul_f32_e32 v115, 0xbfb8aa3b, v109
	v_mul_f32_e32 v116, 0xbfb8aa3b, v110
	v_mul_f32_e32 v117, 0xbfb8aa3b, v111
	v_mul_f32_e32 v118, 0xbfb8aa3b, v104
	v_mul_f32_e32 v119, 0xbfb8aa3b, v105
	v_mul_f32_e32 v120, 0xbfb8aa3b, v106
	v_mul_f32_e32 v121, 0xbfb8aa3b, v107
	v_exp_f32_e32 v114, v114
	v_exp_f32_e32 v115, v115
	v_exp_f32_e32 v116, v116
	v_exp_f32_e32 v117, v117
	v_exp_f32_e32 v118, v118
	v_exp_f32_e32 v119, v119
	v_exp_f32_e32 v120, v120
	v_exp_f32_e32 v121, v121
	v_add_f32_e32 v114, 1.0, v114
	v_add_f32_e32 v115, 1.0, v115
	v_add_f32_e32 v116, 1.0, v116
	v_add_f32_e32 v117, 1.0, v117
	v_add_f32_e32 v118, 1.0, v118
	v_add_f32_e32 v119, 1.0, v119
	v_add_f32_e32 v120, 1.0, v120
	v_add_f32_e32 v121, 1.0, v121
	v_rcp_f32_e32 v114, v114
	v_rcp_f32_e32 v115, v115
	v_rcp_f32_e32 v116, v116
	v_rcp_f32_e32 v117, v117
	v_rcp_f32_e32 v118, v118
	v_rcp_f32_e32 v119, v119
	v_rcp_f32_e32 v120, v120
	v_rcp_f32_e32 v121, v121
	v_pk_mul_f32 v[108:109], v[108:109], v[114:115]
	v_pk_mul_f32 v[110:111], v[110:111], v[116:117]
	v_pk_mul_f32 v[104:105], v[104:105], v[118:119]
	v_pk_mul_f32 v[106:107], v[106:107], v[120:121]
	v_pk_mul_f32 v[100:101], v[100:101], v[108:109]
	v_pk_mul_f32 v[102:103], v[102:103], v[110:111]
	v_pk_mul_f32 v[104:105], v[96:97], v[104:105]
	v_pk_mul_f32 v[106:107], v[98:99], v[106:107]
	v_cvt_pk_bf16_f32 v96, v100, v101
	v_cvt_pk_bf16_f32 v97, v102, v103
	v_cvt_pk_bf16_f32 v98, v104, v105
	v_cvt_pk_bf16_f32 v99, v106, v107
	global_store_dwordx4 v[112:113], v[96:99], off nt
	s_nop 1
	v_fmamk_f32 v96, v248, 0x3a800000, v171
	v_mul_f32_e32 v97, 0x4b800000, v96
	v_cmp_gt_f32_e32 vcc, s40, v96
	s_nop 1
	v_cndmask_b32_e32 v96, v96, v97, vcc
	v_rsq_f32_e32 v98, v96
	v_lshl_add_u64 v[96:97], s[18:19], 0, v[144:145]
	v_lshl_add_u64 v[96:97], v[96:97], 0, v[136:137]
	v_mul_f32_e32 v99, 0x45800000, v98
	v_cndmask_b32_e32 v98, v98, v99, vcc
	v_pk_mul_f32 v[92:93], v[92:93], v[98:99] op_sel_hi:[1,0]
	v_pk_mul_f32 v[94:95], v[94:95], v[98:99] op_sel_hi:[1,0]
	v_pk_mul_f32 v[88:89], v[88:89], v[98:99] op_sel_hi:[1,0]
	v_pk_mul_f32 v[90:91], v[90:91], v[98:99] op_sel_hi:[1,0]
	v_pk_mul_f32 v[84:85], v[84:85], v[98:99] op_sel_hi:[1,0]
	v_pk_mul_f32 v[86:87], v[86:87], v[98:99] op_sel_hi:[1,0]
	v_pk_mul_f32 v[80:81], v[80:81], v[98:99] op_sel_hi:[1,0]
	v_pk_mul_f32 v[82:83], v[82:83], v[98:99] op_sel_hi:[1,0]
	v_mul_f32_e32 v98, 0xbfb8aa3b, v92
	v_mul_f32_e32 v99, 0xbfb8aa3b, v93
	v_mul_f32_e32 v100, 0xbfb8aa3b, v94
	v_mul_f32_e32 v101, 0xbfb8aa3b, v95
	v_mul_f32_e32 v102, 0xbfb8aa3b, v88
	v_mul_f32_e32 v103, 0xbfb8aa3b, v89
	v_mul_f32_e32 v104, 0xbfb8aa3b, v90
	v_mul_f32_e32 v105, 0xbfb8aa3b, v91
	v_exp_f32_e32 v98, v98
	v_exp_f32_e32 v99, v99
	v_exp_f32_e32 v100, v100
	v_exp_f32_e32 v101, v101
	v_exp_f32_e32 v102, v102
	v_exp_f32_e32 v103, v103
	v_exp_f32_e32 v104, v104
	v_exp_f32_e32 v105, v105
	v_add_f32_e32 v98, 1.0, v98
	v_add_f32_e32 v99, 1.0, v99
	v_add_f32_e32 v100, 1.0, v100
	v_add_f32_e32 v101, 1.0, v101
	v_add_f32_e32 v102, 1.0, v102
	v_add_f32_e32 v103, 1.0, v103
	v_add_f32_e32 v104, 1.0, v104
	v_add_f32_e32 v105, 1.0, v105
	v_rcp_f32_e32 v98, v98
	v_rcp_f32_e32 v99, v99
	v_rcp_f32_e32 v100, v100
	v_rcp_f32_e32 v101, v101
	v_rcp_f32_e32 v102, v102
	v_rcp_f32_e32 v103, v103
	v_rcp_f32_e32 v104, v104
	v_rcp_f32_e32 v105, v105
	v_pk_mul_f32 v[92:93], v[92:93], v[98:99]
	v_pk_mul_f32 v[94:95], v[94:95], v[100:101]
	v_pk_mul_f32 v[88:89], v[88:89], v[102:103]
	v_pk_mul_f32 v[90:91], v[90:91], v[104:105]
	v_pk_mul_f32 v[84:85], v[84:85], v[92:93]
	v_pk_mul_f32 v[86:87], v[86:87], v[94:95]
	v_pk_mul_f32 v[88:89], v[80:81], v[88:89]
	v_pk_mul_f32 v[90:91], v[82:83], v[90:91]
	v_cvt_pk_bf16_f32 v80, v84, v85
	v_cvt_pk_bf16_f32 v81, v86, v87
	v_cvt_pk_bf16_f32 v82, v88, v89
	v_cvt_pk_bf16_f32 v83, v90, v91
	global_store_dwordx4 v[96:97], v[80:83], off nt
	s_nop 1
	s_nop 0
	v_add_u32_e32 v80, 0x80, v164
	v_ashrrev_i32_e32 v81, 31, v80
	v_lshl_add_u64 v[80:81], v[80:81], 2, s[6:7]
	v_fmamk_f32 v82, v249, 0x3a800000, v171
	v_mul_f32_e32 v83, 0x4b800000, v82
	v_cmp_gt_f32_e32 vcc, s40, v82
	s_nop 1
	v_cndmask_b32_e32 v82, v82, v83, vcc
	v_rsq_f32_e32 v84, v82
	v_lshl_add_u64 v[82:83], s[18:19], 0, v[146:147]
	v_lshl_add_u64 v[82:83], v[82:83], 0, v[136:137]
	v_mul_f32_e32 v85, 0x45800000, v84
	v_cndmask_b32_e32 v84, v84, v85, vcc
	v_pk_mul_f32 v[76:77], v[76:77], v[84:85] op_sel_hi:[1,0]
	v_pk_mul_f32 v[78:79], v[78:79], v[84:85] op_sel_hi:[1,0]
	v_pk_mul_f32 v[72:73], v[72:73], v[84:85] op_sel_hi:[1,0]
	v_pk_mul_f32 v[74:75], v[74:75], v[84:85] op_sel_hi:[1,0]
	v_pk_mul_f32 v[68:69], v[68:69], v[84:85] op_sel_hi:[1,0]
	v_pk_mul_f32 v[70:71], v[70:71], v[84:85] op_sel_hi:[1,0]
	v_pk_mul_f32 v[64:65], v[64:65], v[84:85] op_sel_hi:[1,0]
	v_pk_mul_f32 v[66:67], v[66:67], v[84:85] op_sel_hi:[1,0]
	v_mul_f32_e32 v84, 0xbfb8aa3b, v76
	v_mul_f32_e32 v85, 0xbfb8aa3b, v77
	v_mul_f32_e32 v86, 0xbfb8aa3b, v78
	v_mul_f32_e32 v87, 0xbfb8aa3b, v79
	v_mul_f32_e32 v88, 0xbfb8aa3b, v72
	v_mul_f32_e32 v89, 0xbfb8aa3b, v73
	v_mul_f32_e32 v90, 0xbfb8aa3b, v74
	v_mul_f32_e32 v91, 0xbfb8aa3b, v75
	v_exp_f32_e32 v84, v84
	v_exp_f32_e32 v85, v85
	v_exp_f32_e32 v86, v86
	v_exp_f32_e32 v87, v87
	v_exp_f32_e32 v88, v88
	v_exp_f32_e32 v89, v89
	v_exp_f32_e32 v90, v90
	v_exp_f32_e32 v91, v91
	v_add_f32_e32 v84, 1.0, v84
	v_add_f32_e32 v85, 1.0, v85
	v_add_f32_e32 v86, 1.0, v86
	v_add_f32_e32 v87, 1.0, v87
	v_add_f32_e32 v88, 1.0, v88
	v_add_f32_e32 v89, 1.0, v89
	v_add_f32_e32 v90, 1.0, v90
	v_add_f32_e32 v91, 1.0, v91
	v_rcp_f32_e32 v84, v84
	v_rcp_f32_e32 v85, v85
	v_rcp_f32_e32 v86, v86
	v_rcp_f32_e32 v87, v87
	v_rcp_f32_e32 v88, v88
	v_rcp_f32_e32 v89, v89
	v_rcp_f32_e32 v90, v90
	v_rcp_f32_e32 v91, v91
	v_pk_mul_f32 v[76:77], v[76:77], v[84:85]
	v_pk_mul_f32 v[78:79], v[78:79], v[86:87]
	v_pk_mul_f32 v[72:73], v[72:73], v[88:89]
	v_pk_mul_f32 v[74:75], v[74:75], v[90:91]
	v_pk_mul_f32 v[68:69], v[68:69], v[76:77]
	v_pk_mul_f32 v[70:71], v[70:71], v[78:79]
	v_pk_mul_f32 v[72:73], v[64:65], v[72:73]
	v_pk_mul_f32 v[74:75], v[66:67], v[74:75]
	v_cvt_pk_bf16_f32 v64, v68, v69
	v_cvt_pk_bf16_f32 v65, v70, v71
	v_cvt_pk_bf16_f32 v66, v72, v73
	v_cvt_pk_bf16_f32 v67, v74, v75
	global_store_dwordx4 v[82:83], v[64:67], off nt
	s_nop 1
	s_nop 0
	v_add_u32_e32 v64, 0x90, v164
	v_ashrrev_i32_e32 v65, 31, v64
	v_lshl_add_u64 v[64:65], v[64:65], 2, s[6:7]
	v_fmamk_f32 v66, v250, 0x3a800000, v171
	v_mul_f32_e32 v67, 0x4b800000, v66
	v_cmp_gt_f32_e32 vcc, s40, v66
	s_nop 1
	v_cndmask_b32_e32 v66, v66, v67, vcc
	v_rsq_f32_e32 v68, v66
	v_lshl_add_u64 v[66:67], s[18:19], 0, v[148:149]
	v_lshl_add_u64 v[66:67], v[66:67], 0, v[136:137]
	v_mul_f32_e32 v69, 0x45800000, v68
	v_cndmask_b32_e32 v68, v68, v69, vcc
	v_pk_mul_f32 v[60:61], v[60:61], v[68:69] op_sel_hi:[1,0]
	v_pk_mul_f32 v[62:63], v[62:63], v[68:69] op_sel_hi:[1,0]
	v_pk_mul_f32 v[56:57], v[56:57], v[68:69] op_sel_hi:[1,0]
	v_pk_mul_f32 v[58:59], v[58:59], v[68:69] op_sel_hi:[1,0]
	v_pk_mul_f32 v[52:53], v[52:53], v[68:69] op_sel_hi:[1,0]
	v_pk_mul_f32 v[54:55], v[54:55], v[68:69] op_sel_hi:[1,0]
	v_pk_mul_f32 v[48:49], v[48:49], v[68:69] op_sel_hi:[1,0]
	v_pk_mul_f32 v[50:51], v[50:51], v[68:69] op_sel_hi:[1,0]
	v_mul_f32_e32 v68, 0xbfb8aa3b, v60
	v_mul_f32_e32 v69, 0xbfb8aa3b, v61
	v_mul_f32_e32 v70, 0xbfb8aa3b, v62
	v_mul_f32_e32 v71, 0xbfb8aa3b, v63
	v_mul_f32_e32 v72, 0xbfb8aa3b, v56
	v_mul_f32_e32 v73, 0xbfb8aa3b, v57
	v_mul_f32_e32 v74, 0xbfb8aa3b, v58
	v_mul_f32_e32 v75, 0xbfb8aa3b, v59
	v_exp_f32_e32 v68, v68
	v_exp_f32_e32 v69, v69
	v_exp_f32_e32 v70, v70
	v_exp_f32_e32 v71, v71
	v_exp_f32_e32 v72, v72
	v_exp_f32_e32 v73, v73
	v_exp_f32_e32 v74, v74
	v_exp_f32_e32 v75, v75
	v_add_f32_e32 v68, 1.0, v68
	v_add_f32_e32 v69, 1.0, v69
	v_add_f32_e32 v70, 1.0, v70
	v_add_f32_e32 v71, 1.0, v71
	v_add_f32_e32 v72, 1.0, v72
	v_add_f32_e32 v73, 1.0, v73
	v_add_f32_e32 v74, 1.0, v74
	v_add_f32_e32 v75, 1.0, v75
	v_rcp_f32_e32 v68, v68
	v_rcp_f32_e32 v69, v69
	v_rcp_f32_e32 v70, v70
	v_rcp_f32_e32 v71, v71
	v_rcp_f32_e32 v72, v72
	v_rcp_f32_e32 v73, v73
	v_rcp_f32_e32 v74, v74
	v_rcp_f32_e32 v75, v75
	v_pk_mul_f32 v[60:61], v[60:61], v[68:69]
	v_pk_mul_f32 v[62:63], v[62:63], v[70:71]
	v_pk_mul_f32 v[56:57], v[56:57], v[72:73]
	v_pk_mul_f32 v[58:59], v[58:59], v[74:75]
	v_pk_mul_f32 v[52:53], v[52:53], v[60:61]
	v_pk_mul_f32 v[54:55], v[54:55], v[62:63]
	v_pk_mul_f32 v[56:57], v[48:49], v[56:57]
	v_pk_mul_f32 v[58:59], v[50:51], v[58:59]
	v_cvt_pk_bf16_f32 v48, v52, v53
	v_cvt_pk_bf16_f32 v49, v54, v55
	v_cvt_pk_bf16_f32 v50, v56, v57
	v_cvt_pk_bf16_f32 v51, v58, v59
	global_store_dwordx4 v[66:67], v[48:51], off nt
	s_nop 1
	s_nop 0
	v_add_u32_e32 v48, 0xa0, v164
	v_ashrrev_i32_e32 v49, 31, v48
	v_lshl_add_u64 v[48:49], v[48:49], 2, s[6:7]
	v_fmamk_f32 v50, v251, 0x3a800000, v171
	v_mul_f32_e32 v51, 0x4b800000, v50
	v_cmp_gt_f32_e32 vcc, s40, v50
	s_nop 1
	v_cndmask_b32_e32 v50, v50, v51, vcc
	v_rsq_f32_e32 v52, v50
	v_lshl_add_u64 v[50:51], s[18:19], 0, v[150:151]
	v_lshl_add_u64 v[50:51], v[50:51], 0, v[136:137]
	v_mul_f32_e32 v53, 0x45800000, v52
	v_cndmask_b32_e32 v52, v52, v53, vcc
	v_pk_mul_f32 v[44:45], v[44:45], v[52:53] op_sel_hi:[1,0]
	v_pk_mul_f32 v[46:47], v[46:47], v[52:53] op_sel_hi:[1,0]
	v_pk_mul_f32 v[40:41], v[40:41], v[52:53] op_sel_hi:[1,0]
	v_pk_mul_f32 v[42:43], v[42:43], v[52:53] op_sel_hi:[1,0]
	v_pk_mul_f32 v[36:37], v[36:37], v[52:53] op_sel_hi:[1,0]
	v_pk_mul_f32 v[38:39], v[38:39], v[52:53] op_sel_hi:[1,0]
	v_pk_mul_f32 v[32:33], v[32:33], v[52:53] op_sel_hi:[1,0]
	v_pk_mul_f32 v[34:35], v[34:35], v[52:53] op_sel_hi:[1,0]
	v_mul_f32_e32 v52, 0xbfb8aa3b, v44
	v_mul_f32_e32 v53, 0xbfb8aa3b, v45
	v_mul_f32_e32 v54, 0xbfb8aa3b, v46
	v_mul_f32_e32 v55, 0xbfb8aa3b, v47
	v_mul_f32_e32 v56, 0xbfb8aa3b, v40
	v_mul_f32_e32 v57, 0xbfb8aa3b, v41
	v_mul_f32_e32 v58, 0xbfb8aa3b, v42
	v_mul_f32_e32 v59, 0xbfb8aa3b, v43
	v_exp_f32_e32 v52, v52
	v_exp_f32_e32 v53, v53
	v_exp_f32_e32 v54, v54
	v_exp_f32_e32 v55, v55
	v_exp_f32_e32 v56, v56
	v_exp_f32_e32 v57, v57
	v_exp_f32_e32 v58, v58
	v_exp_f32_e32 v59, v59
	v_add_f32_e32 v52, 1.0, v52
	v_add_f32_e32 v53, 1.0, v53
	v_add_f32_e32 v54, 1.0, v54
	v_add_f32_e32 v55, 1.0, v55
	v_add_f32_e32 v56, 1.0, v56
	v_add_f32_e32 v57, 1.0, v57
	v_add_f32_e32 v58, 1.0, v58
	v_add_f32_e32 v59, 1.0, v59
	v_rcp_f32_e32 v52, v52
	v_rcp_f32_e32 v53, v53
	v_rcp_f32_e32 v54, v54
	v_rcp_f32_e32 v55, v55
	v_rcp_f32_e32 v56, v56
	v_rcp_f32_e32 v57, v57
	v_rcp_f32_e32 v58, v58
	v_rcp_f32_e32 v59, v59
	v_pk_mul_f32 v[44:45], v[44:45], v[52:53]
	v_pk_mul_f32 v[46:47], v[46:47], v[54:55]
	v_pk_mul_f32 v[40:41], v[40:41], v[56:57]
	v_pk_mul_f32 v[42:43], v[42:43], v[58:59]
	v_pk_mul_f32 v[36:37], v[36:37], v[44:45]
	v_pk_mul_f32 v[38:39], v[38:39], v[46:47]
	v_pk_mul_f32 v[40:41], v[32:33], v[40:41]
	v_pk_mul_f32 v[42:43], v[34:35], v[42:43]
	v_cvt_pk_bf16_f32 v32, v36, v37
	v_cvt_pk_bf16_f32 v33, v38, v39
	v_cvt_pk_bf16_f32 v34, v40, v41
	v_cvt_pk_bf16_f32 v35, v42, v43
	global_store_dwordx4 v[50:51], v[32:35], off nt
	s_nop 1
	s_nop 0
	v_add_u32_e32 v32, 0xb0, v164
	v_ashrrev_i32_e32 v33, 31, v32
	v_lshl_add_u64 v[32:33], v[32:33], 2, s[6:7]
	v_fmamk_f32 v34, v252, 0x3a800000, v171
	v_mul_f32_e32 v35, 0x4b800000, v34
	v_cmp_gt_f32_e32 vcc, s40, v34
	s_nop 1
	v_cndmask_b32_e32 v34, v34, v35, vcc
	v_rsq_f32_e32 v36, v34
	v_lshl_add_u64 v[34:35], s[18:19], 0, v[152:153]
	v_lshl_add_u64 v[34:35], v[34:35], 0, v[136:137]
	v_mul_f32_e32 v37, 0x45800000, v36
	v_cndmask_b32_e32 v36, v36, v37, vcc
	v_pk_mul_f32 v[28:29], v[28:29], v[36:37] op_sel_hi:[1,0]
	v_pk_mul_f32 v[30:31], v[30:31], v[36:37] op_sel_hi:[1,0]
	v_pk_mul_f32 v[24:25], v[24:25], v[36:37] op_sel_hi:[1,0]
	v_pk_mul_f32 v[26:27], v[26:27], v[36:37] op_sel_hi:[1,0]
	v_pk_mul_f32 v[20:21], v[20:21], v[36:37] op_sel_hi:[1,0]
	v_pk_mul_f32 v[22:23], v[22:23], v[36:37] op_sel_hi:[1,0]
	v_pk_mul_f32 v[16:17], v[16:17], v[36:37] op_sel_hi:[1,0]
	v_pk_mul_f32 v[18:19], v[18:19], v[36:37] op_sel_hi:[1,0]
	v_mul_f32_e32 v36, 0xbfb8aa3b, v28
	v_mul_f32_e32 v37, 0xbfb8aa3b, v29
	v_mul_f32_e32 v38, 0xbfb8aa3b, v30
	v_mul_f32_e32 v39, 0xbfb8aa3b, v31
	v_mul_f32_e32 v40, 0xbfb8aa3b, v24
	v_mul_f32_e32 v41, 0xbfb8aa3b, v25
	v_mul_f32_e32 v42, 0xbfb8aa3b, v26
	v_mul_f32_e32 v43, 0xbfb8aa3b, v27
	v_exp_f32_e32 v36, v36
	v_exp_f32_e32 v37, v37
	v_exp_f32_e32 v38, v38
	v_exp_f32_e32 v39, v39
	v_exp_f32_e32 v40, v40
	v_exp_f32_e32 v41, v41
	v_exp_f32_e32 v42, v42
	v_exp_f32_e32 v43, v43
	v_add_f32_e32 v36, 1.0, v36
	v_add_f32_e32 v37, 1.0, v37
	v_add_f32_e32 v38, 1.0, v38
	v_add_f32_e32 v39, 1.0, v39
	v_add_f32_e32 v40, 1.0, v40
	v_add_f32_e32 v41, 1.0, v41
	v_add_f32_e32 v42, 1.0, v42
	v_add_f32_e32 v43, 1.0, v43
	v_rcp_f32_e32 v36, v36
	v_rcp_f32_e32 v37, v37
	v_rcp_f32_e32 v38, v38
	v_rcp_f32_e32 v39, v39
	v_rcp_f32_e32 v40, v40
	v_rcp_f32_e32 v41, v41
	v_rcp_f32_e32 v42, v42
	v_rcp_f32_e32 v43, v43
	v_pk_mul_f32 v[28:29], v[28:29], v[36:37]
	v_pk_mul_f32 v[30:31], v[30:31], v[38:39]
	v_pk_mul_f32 v[24:25], v[24:25], v[40:41]
	v_pk_mul_f32 v[26:27], v[26:27], v[42:43]
	v_pk_mul_f32 v[20:21], v[20:21], v[28:29]
	v_pk_mul_f32 v[22:23], v[22:23], v[30:31]
	v_pk_mul_f32 v[24:25], v[16:17], v[24:25]
	v_pk_mul_f32 v[26:27], v[18:19], v[26:27]
	v_cvt_pk_bf16_f32 v16, v20, v21
	v_cvt_pk_bf16_f32 v17, v22, v23
	v_cvt_pk_bf16_f32 v18, v24, v25
	v_cvt_pk_bf16_f32 v19, v26, v27
	global_store_dwordx4 v[34:35], v[16:19], off nt
	s_nop 1
	s_andn2_b64 vcc, exec, s[2:3]
	s_mov_b64 s[2:3], -1
	v_fmamk_f32 v16, v253, 0x3a800000, v171
	v_mul_f32_e32 v17, 0x4b800000, v16
	v_cmp_gt_f32_e64 s[4:5], s40, v16
	s_nop 1
	v_cndmask_b32_e64 v16, v16, v17, s[4:5]
	v_rsq_f32_e32 v18, v16
	v_lshl_add_u64 v[16:17], s[18:19], 0, v[154:155]
	v_lshl_add_u64 v[16:17], v[16:17], 0, v[136:137]
	v_mul_f32_e32 v19, 0x45800000, v18
	v_cndmask_b32_e64 v18, v18, v19, s[4:5]
	v_pk_mul_f32 v[12:13], v[12:13], v[18:19] op_sel_hi:[1,0]
	v_pk_mul_f32 v[14:15], v[14:15], v[18:19] op_sel_hi:[1,0]
	v_pk_mul_f32 v[8:9], v[8:9], v[18:19] op_sel_hi:[1,0]
	v_pk_mul_f32 v[10:11], v[10:11], v[18:19] op_sel_hi:[1,0]
	v_pk_mul_f32 v[4:5], v[4:5], v[18:19] op_sel_hi:[1,0]
	v_pk_mul_f32 v[6:7], v[6:7], v[18:19] op_sel_hi:[1,0]
	v_pk_mul_f32 v[0:1], v[0:1], v[18:19] op_sel_hi:[1,0]
	v_pk_mul_f32 v[2:3], v[2:3], v[18:19] op_sel_hi:[1,0]
	v_mul_f32_e32 v18, 0xbfb8aa3b, v12
	v_mul_f32_e32 v19, 0xbfb8aa3b, v13
	v_mul_f32_e32 v20, 0xbfb8aa3b, v14
	v_mul_f32_e32 v21, 0xbfb8aa3b, v15
	v_mul_f32_e32 v22, 0xbfb8aa3b, v8
	v_mul_f32_e32 v23, 0xbfb8aa3b, v9
	v_mul_f32_e32 v24, 0xbfb8aa3b, v10
	v_mul_f32_e32 v25, 0xbfb8aa3b, v11
	v_exp_f32_e32 v18, v18
	v_exp_f32_e32 v19, v19
	v_exp_f32_e32 v20, v20
	v_exp_f32_e32 v21, v21
	v_exp_f32_e32 v22, v22
	v_exp_f32_e32 v23, v23
	v_exp_f32_e32 v24, v24
	v_exp_f32_e32 v25, v25
	v_add_f32_e32 v18, 1.0, v18
	v_add_f32_e32 v19, 1.0, v19
	v_add_f32_e32 v20, 1.0, v20
	v_add_f32_e32 v21, 1.0, v21
	v_add_f32_e32 v22, 1.0, v22
	v_add_f32_e32 v23, 1.0, v23
	v_add_f32_e32 v24, 1.0, v24
	v_add_f32_e32 v25, 1.0, v25
	v_rcp_f32_e32 v18, v18
	v_rcp_f32_e32 v19, v19
	v_rcp_f32_e32 v20, v20
	v_rcp_f32_e32 v21, v21
	v_rcp_f32_e32 v22, v22
	v_rcp_f32_e32 v23, v23
	v_rcp_f32_e32 v24, v24
	v_rcp_f32_e32 v25, v25
	v_pk_mul_f32 v[12:13], v[12:13], v[18:19]
	v_pk_mul_f32 v[14:15], v[14:15], v[20:21]
	v_pk_mul_f32 v[8:9], v[8:9], v[22:23]
	v_pk_mul_f32 v[10:11], v[10:11], v[24:25]
	v_pk_mul_f32 v[4:5], v[4:5], v[12:13]
	v_pk_mul_f32 v[6:7], v[6:7], v[14:15]
	v_pk_mul_f32 v[8:9], v[0:1], v[8:9]
	v_pk_mul_f32 v[10:11], v[2:3], v[10:11]
	v_cvt_pk_bf16_f32 v0, v4, v5
	v_cvt_pk_bf16_f32 v1, v6, v7
	v_cvt_pk_bf16_f32 v2, v8, v9
	v_cvt_pk_bf16_f32 v3, v10, v11
	global_store_dwordx4 v[16:17], v[0:3], off nt
	s_cbranch_vccnz .LBB0_1623
	s_andn2_b64 vcc, exec, s[0:1]
	s_cbranch_vccnz .LBB0_1622
	s_barrier
	s_branch .LBB0_1622
